# phase 13 (FFN conv+SiLU gate) hand-written: wave = 256 channels x fixed run set, weights loaded once, 18-slot rolling load pipeline overlapping next run's loads with compute/stores
# speedup vs baseline: 1.0217x; 1.0217x over previous
.LBB0_34:
	s_cmp_gt_i32 s70, 12
	s_mov_b64 s[4:5], -1
	s_cbranch_scc0 .LBB0_119
	s_mov_b32 s0, 0x63000
	v_cmp_gt_i32_e32 vcc, s0, v176
	s_and_saveexec_b64 s[18:19], vcc
	s_cbranch_execz .LBB0_118
	v_readfirstlane_b32 s0, v164
	s_cmpk_gt_u32 s0, 0x7fd
	s_cbranch_scc1 .Lffn_done
	v_readlane_b32 s2, v254, 56
	v_readlane_b32 s3, v254, 57
	s_mul_hi_u32 s34, s0, 0x1745d175
	s_mul_i32 s1, s34, 11
	s_sub_i32 s1, s0, s1
	s_lshl_b32 s1, s1, 8
	s_load_dwordx2 s[30:31], s[2:3], 0x108
	s_load_dwordx4 s[24:27], s[2:3], 0xe0
	s_load_dwordx2 s[28:29], s[2:3], 0x30
	s_load_dwordx2 s[22:23], s[2:3], 0x100
	v_and_b32_e32 v2, 63, v174
	v_lshl_add_u32 v2, v2, 2, s1
	v_lshlrev_b32_e32 v28, 1, v2
	v_add_u32_e32 v29, 0x1600, v28
	v_lshlrev_b32_e32 v30, 2, v2
	v_add_u32_e32 v31, 0x2c00, v30
	v_mov_b32_e32 v160, 0xbfb8aa3b
	v_mov_b32_e32 v161, 0xbfb8aa3b
	v_mov_b32_e32 v162, 1.0
	v_mov_b32_e32 v163, 1.0
	s_cmpk_lt_u32 s34, 0x5e
	s_cselect_b32 s35, 6, 5
	s_mul_i32 s37, s35, 0xba
	s_add_i32 s37, s37, s34
	s_sub_i32 s37, s37, 0x400
	s_cmpk_lt_u32 s34, 0x24
	s_cselect_b32 s36, 1, 0
	s_cmpk_gt_u32 s34, 0x5d
	s_cselect_b32 s1, 1, 0
	s_or_b32 s36, s36, s1
	s_waitcnt lgkmcnt(0)
	global_load_dwordx4 v[32:35], v30, s[24:25]
	global_load_dwordx4 v[48:51], v31, s[24:25]
	s_add_u32 s4, s24, 0x5800
	s_addc_u32 s5, s25, 0
	global_load_dwordx4 v[36:39], v30, s[4:5]
	global_load_dwordx4 v[52:55], v31, s[4:5]
	s_add_u32 s4, s4, 0x5800
	s_addc_u32 s5, s5, 0
	global_load_dwordx4 v[40:43], v30, s[4:5]
	global_load_dwordx4 v[56:59], v31, s[4:5]
	global_load_dwordx4 v[44:47], v30, s[26:27]
	global_load_dwordx4 v[60:63], v31, s[26:27]
	s_cmp_eq_u32 s36, 0
	s_cbranch_scc1 .Lffn_nosld
	s_mul_i32 s0, s37, 0xb000
	s_add_u32 s4, s28, s0
	s_addc_u32 s5, s29, 0
	global_load_dwordx4 v[178:181], v30, s[4:5]
	global_load_dwordx4 v[182:185], v31, s[4:5]
	s_add_u32 s4, s4, 0x5800
	s_addc_u32 s5, s5, 0
	global_load_dwordx4 v[186:189], v30, s[4:5]
	global_load_dwordx4 v[190:193], v31, s[4:5]
	s_add_u32 s4, s30, 0x9408000
	s_addc_u32 s5, s31, 0
	s_add_u32 s4, s4, 0xb000000
	s_addc_u32 s5, s5, 0
	s_add_u32 s4, s4, s0
	s_addc_u32 s5, s5, 0
	global_load_dwordx2 v[194:195], v28, s[4:5] nt
	global_load_dwordx2 v[196:197], v29, s[4:5] nt
	s_add_u32 s4, s4, 0x2c00
	s_addc_u32 s5, s5, 0
	global_load_dwordx2 v[198:199], v28, s[4:5] nt
	global_load_dwordx2 v[200:201], v29, s[4:5] nt
	s_add_u32 s4, s4, 0x2c00
	s_addc_u32 s5, s5, 0
	global_load_dwordx2 v[202:203], v28, s[4:5] nt
	global_load_dwordx2 v[204:205], v29, s[4:5] nt
	s_add_u32 s4, s4, 0x2c00
	s_addc_u32 s5, s5, 0
	global_load_dwordx2 v[206:207], v28, s[4:5] nt
	global_load_dwordx2 v[208:209], v29, s[4:5] nt
.Lffn_nosld:
	s_add_u32 s8, s30, 0x9408000
	s_addc_u32 s9, s31, 0
	s_mul_i32 s0, s34, 0x2c000
	s_add_u32 s8, s8, s0
	s_addc_u32 s9, s9, 0
	s_sub_u32 s8, s8, 0x5800
	s_subb_u32 s9, s9, 0
	s_add_u32 s10, s30, 0x14988000
	s_addc_u32 s11, s31, 0
	s_mul_i32 s0, s34, 0x16000
	s_add_u32 s10, s10, s0
	s_addc_u32 s11, s11, 0
	s_mov_b32 s13, s34
	global_load_dwordx2 v[64:65], v28, s[8:9] nt
	global_load_dwordx2 v[66:67], v29, s[8:9] nt
	s_add_u32 s8, s8, 0x2c00
	s_addc_u32 s9, s9, 0
	global_load_dwordx2 v[68:69], v28, s[8:9] nt
	global_load_dwordx2 v[70:71], v29, s[8:9] nt
	s_add_u32 s8, s8, 0x2c00
	s_addc_u32 s9, s9, 0
	global_load_dwordx2 v[72:73], v28, s[8:9] nt
	global_load_dwordx2 v[74:75], v29, s[8:9] nt
	s_add_u32 s8, s8, 0x2c00
	s_addc_u32 s9, s9, 0
	global_load_dwordx2 v[76:77], v28, s[8:9] nt
	global_load_dwordx2 v[78:79], v29, s[8:9] nt
	s_add_u32 s8, s8, 0x2c00
	s_addc_u32 s9, s9, 0
	global_load_dwordx2 v[80:81], v28, s[8:9] nt
	global_load_dwordx2 v[82:83], v29, s[8:9] nt
	s_add_u32 s8, s8, 0x2c00
	s_addc_u32 s9, s9, 0
	global_load_dwordx2 v[84:85], v28, s[8:9] nt
	global_load_dwordx2 v[86:87], v29, s[8:9] nt
	s_add_u32 s8, s8, 0x2c00
	s_addc_u32 s9, s9, 0
	global_load_dwordx2 v[88:89], v28, s[8:9] nt
	global_load_dwordx2 v[90:91], v29, s[8:9] nt
	s_add_u32 s8, s8, 0x2c00
	s_addc_u32 s9, s9, 0
	global_load_dwordx2 v[92:93], v28, s[8:9] nt
	global_load_dwordx2 v[94:95], v29, s[8:9] nt
	s_add_u32 s8, s8, 0x2c00
	s_addc_u32 s9, s9, 0
	global_load_dwordx2 v[96:97], v28, s[8:9] nt
	global_load_dwordx2 v[98:99], v29, s[8:9] nt
	s_add_u32 s8, s8, 0x2c00
	s_addc_u32 s9, s9, 0
	global_load_dwordx2 v[100:101], v28, s[8:9] nt
	global_load_dwordx2 v[102:103], v29, s[8:9] nt
	s_add_u32 s8, s8, 0x2c00
	s_addc_u32 s9, s9, 0
	global_load_dwordx2 v[104:105], v28, s[8:9] nt
	global_load_dwordx2 v[106:107], v29, s[8:9] nt
	s_add_u32 s8, s8, 0x2c00
	s_addc_u32 s9, s9, 0
	global_load_dwordx2 v[108:109], v28, s[8:9] nt
	global_load_dwordx2 v[110:111], v29, s[8:9] nt
	s_add_u32 s8, s8, 0x2c00
	s_addc_u32 s9, s9, 0
	global_load_dwordx2 v[112:113], v28, s[8:9] nt
	global_load_dwordx2 v[114:115], v29, s[8:9] nt
	s_add_u32 s8, s8, 0x2c00
	s_addc_u32 s9, s9, 0
	global_load_dwordx2 v[116:117], v28, s[8:9] nt
	global_load_dwordx2 v[118:119], v29, s[8:9] nt
	s_add_u32 s8, s8, 0x2c00
	s_addc_u32 s9, s9, 0
	global_load_dwordx2 v[120:121], v28, s[8:9] nt
	global_load_dwordx2 v[122:123], v29, s[8:9] nt
	s_add_u32 s8, s8, 0x2c00
	s_addc_u32 s9, s9, 0
	global_load_dwordx2 v[124:125], v28, s[8:9] nt
	global_load_dwordx2 v[126:127], v29, s[8:9] nt
	s_add_u32 s8, s8, 0x2c00
	s_addc_u32 s9, s9, 0
	global_load_dwordx2 v[128:129], v28, s[8:9] nt
	global_load_dwordx2 v[130:131], v29, s[8:9] nt
	s_add_u32 s8, s8, 0x2c00
	s_addc_u32 s9, s9, 0
	global_load_dwordx2 v[132:133], v28, s[8:9] nt
	global_load_dwordx2 v[134:135], v29, s[8:9] nt
	s_add_u32 s8, s8, 0x2c00
	s_addc_u32 s9, s9, 0
	s_add_u32 s8, s8, 0x1fc6800
	s_addc_u32 s9, s9, 0
	s_sub_i32 s12, s35, 1
.Lffn_loop:
	s_and_b32 s0, s13, 0x7f
	s_cmp_eq_u32 s0, 0
	s_cselect_b32 s14, 0, -1
	s_cmpk_eq_u32 s0, 0x7f
	s_cselect_b32 s15, 1, 0
	s_waitcnt vmcnt(34)
	v_and_b32_e32 v64, s14, v64
	v_and_b32_e32 v65, s14, v65
	v_and_b32_e32 v66, s14, v66
	v_and_b32_e32 v67, s14, v67
	v_lshlrev_b32_e32 v136, 16, v64
	v_and_b32_e32 v137, 0xffff0000, v64
	v_lshlrev_b32_e32 v138, 16, v65
	v_and_b32_e32 v139, 0xffff0000, v65
	v_lshlrev_b32_e32 v140, 16, v66
	v_and_b32_e32 v141, 0xffff0000, v66
	v_lshlrev_b32_e32 v142, 16, v67
	v_and_b32_e32 v143, 0xffff0000, v67
	global_load_dwordx2 v[64:65], v28, s[8:9] nt
	global_load_dwordx2 v[66:67], v29, s[8:9] nt
	s_add_u32 s8, s8, 0x2c00
	s_addc_u32 s9, s9, 0
	s_waitcnt vmcnt(34)
	v_and_b32_e32 v68, s14, v68
	v_and_b32_e32 v69, s14, v69
	v_and_b32_e32 v70, s14, v70
	v_and_b32_e32 v71, s14, v71
	v_lshlrev_b32_e32 v144, 16, v68
	v_and_b32_e32 v145, 0xffff0000, v68
	v_lshlrev_b32_e32 v146, 16, v69
	v_and_b32_e32 v147, 0xffff0000, v69
	v_lshlrev_b32_e32 v148, 16, v70
	v_and_b32_e32 v149, 0xffff0000, v70
	v_lshlrev_b32_e32 v150, 16, v71
	v_and_b32_e32 v151, 0xffff0000, v71
	global_load_dwordx2 v[68:69], v28, s[8:9] nt
	global_load_dwordx2 v[70:71], v29, s[8:9] nt
	s_add_u32 s8, s8, 0x2c00
	s_addc_u32 s9, s9, 0
	s_waitcnt vmcnt(34)
	v_lshlrev_b32_e32 v152, 16, v72
	v_and_b32_e32 v153, 0xffff0000, v72
	v_lshlrev_b32_e32 v154, 16, v73
	v_and_b32_e32 v155, 0xffff0000, v73
	v_lshlrev_b32_e32 v156, 16, v74
	v_and_b32_e32 v157, 0xffff0000, v74
	v_lshlrev_b32_e32 v158, 16, v75
	v_and_b32_e32 v159, 0xffff0000, v75
	global_load_dwordx2 v[72:73], v28, s[8:9] nt
	global_load_dwordx2 v[74:75], v29, s[8:9] nt
	s_add_u32 s8, s8, 0x2c00
	s_addc_u32 s9, s9, 0
	v_pk_fma_f32 v[2:3], v[32:33], v[136:137], v[44:45]
	v_pk_fma_f32 v[4:5], v[34:35], v[138:139], v[46:47]
	v_pk_fma_f32 v[6:7], v[48:49], v[140:141], v[60:61]
	v_pk_fma_f32 v[8:9], v[50:51], v[142:143], v[62:63]
	v_pk_fma_f32 v[2:3], v[36:37], v[144:145], v[2:3]
	v_pk_fma_f32 v[4:5], v[38:39], v[146:147], v[4:5]
	v_pk_fma_f32 v[6:7], v[52:53], v[148:149], v[6:7]
	v_pk_fma_f32 v[8:9], v[54:55], v[150:151], v[8:9]
	v_pk_fma_f32 v[2:3], v[40:41], v[152:153], v[2:3]
	v_pk_fma_f32 v[4:5], v[42:43], v[154:155], v[4:5]
	v_pk_fma_f32 v[6:7], v[56:57], v[156:157], v[6:7]
	v_pk_fma_f32 v[8:9], v[58:59], v[158:159], v[8:9]
	v_pk_mul_f32 v[10:11], v[2:3], v[160:161]
	v_pk_mul_f32 v[12:13], v[4:5], v[160:161]
	v_exp_f32_e32 v10, v10
	v_exp_f32_e32 v11, v11
	v_exp_f32_e32 v12, v12
	v_exp_f32_e32 v13, v13
	v_pk_add_f32 v[10:11], v[10:11], v[162:163]
	v_pk_add_f32 v[12:13], v[12:13], v[162:163]
	v_rcp_f32_e32 v10, v10
	v_rcp_f32_e32 v11, v11
	v_rcp_f32_e32 v12, v12
	v_rcp_f32_e32 v13, v13
	v_pk_mul_f32 v[10:11], v[2:3], v[10:11]
	v_pk_mul_f32 v[12:13], v[4:5], v[12:13]
	v_pk_mul_f32 v[10:11], v[6:7], v[10:11]
	v_pk_mul_f32 v[12:13], v[8:9], v[12:13]
	v_cvt_pk_bf16_f32 v14, v10, v11
	v_cvt_pk_bf16_f32 v15, v12, v13
	global_store_dwordx2 v28, v[14:15], s[10:11]
	s_add_u32 s10, s10, 0x1600
	s_addc_u32 s11, s11, 0
	s_waitcnt vmcnt(35)
	v_lshlrev_b32_e32 v136, 16, v76
	v_and_b32_e32 v137, 0xffff0000, v76
	v_lshlrev_b32_e32 v138, 16, v77
	v_and_b32_e32 v139, 0xffff0000, v77
	v_lshlrev_b32_e32 v140, 16, v78
	v_and_b32_e32 v141, 0xffff0000, v78
	v_lshlrev_b32_e32 v142, 16, v79
	v_and_b32_e32 v143, 0xffff0000, v79
	global_load_dwordx2 v[76:77], v28, s[8:9] nt
	global_load_dwordx2 v[78:79], v29, s[8:9] nt
	s_add_u32 s8, s8, 0x2c00
	s_addc_u32 s9, s9, 0
	v_pk_fma_f32 v[2:3], v[32:33], v[144:145], v[44:45]
	v_pk_fma_f32 v[4:5], v[34:35], v[146:147], v[46:47]
	v_pk_fma_f32 v[6:7], v[48:49], v[148:149], v[60:61]
	v_pk_fma_f32 v[8:9], v[50:51], v[150:151], v[62:63]
	v_pk_fma_f32 v[2:3], v[36:37], v[152:153], v[2:3]
	v_pk_fma_f32 v[4:5], v[38:39], v[154:155], v[4:5]
	v_pk_fma_f32 v[6:7], v[52:53], v[156:157], v[6:7]
	v_pk_fma_f32 v[8:9], v[54:55], v[158:159], v[8:9]
	v_pk_fma_f32 v[2:3], v[40:41], v[136:137], v[2:3]
	v_pk_fma_f32 v[4:5], v[42:43], v[138:139], v[4:5]
	v_pk_fma_f32 v[6:7], v[56:57], v[140:141], v[6:7]
	v_pk_fma_f32 v[8:9], v[58:59], v[142:143], v[8:9]
	v_pk_mul_f32 v[10:11], v[2:3], v[160:161]
	v_pk_mul_f32 v[12:13], v[4:5], v[160:161]
	v_exp_f32_e32 v10, v10
	v_exp_f32_e32 v11, v11
	v_exp_f32_e32 v12, v12
	v_exp_f32_e32 v13, v13
	v_pk_add_f32 v[10:11], v[10:11], v[162:163]
	v_pk_add_f32 v[12:13], v[12:13], v[162:163]
	v_rcp_f32_e32 v10, v10
	v_rcp_f32_e32 v11, v11
	v_rcp_f32_e32 v12, v12
	v_rcp_f32_e32 v13, v13
	v_pk_mul_f32 v[10:11], v[2:3], v[10:11]
	v_pk_mul_f32 v[12:13], v[4:5], v[12:13]
	v_pk_mul_f32 v[10:11], v[6:7], v[10:11]
	v_pk_mul_f32 v[12:13], v[8:9], v[12:13]
	v_cvt_pk_bf16_f32 v14, v10, v11
	v_cvt_pk_bf16_f32 v15, v12, v13
	global_store_dwordx2 v28, v[14:15], s[10:11]
	s_add_u32 s10, s10, 0x1600
	s_addc_u32 s11, s11, 0
	s_waitcnt vmcnt(36)
	v_lshlrev_b32_e32 v144, 16, v80
	v_and_b32_e32 v145, 0xffff0000, v80
	v_lshlrev_b32_e32 v146, 16, v81
	v_and_b32_e32 v147, 0xffff0000, v81
	v_lshlrev_b32_e32 v148, 16, v82
	v_and_b32_e32 v149, 0xffff0000, v82
	v_lshlrev_b32_e32 v150, 16, v83
	v_and_b32_e32 v151, 0xffff0000, v83
	global_load_dwordx2 v[80:81], v28, s[8:9] nt
	global_load_dwordx2 v[82:83], v29, s[8:9] nt
	s_add_u32 s8, s8, 0x2c00
	s_addc_u32 s9, s9, 0
	v_pk_fma_f32 v[2:3], v[32:33], v[152:153], v[44:45]
	v_pk_fma_f32 v[4:5], v[34:35], v[154:155], v[46:47]
	v_pk_fma_f32 v[6:7], v[48:49], v[156:157], v[60:61]
	v_pk_fma_f32 v[8:9], v[50:51], v[158:159], v[62:63]
	v_pk_fma_f32 v[2:3], v[36:37], v[136:137], v[2:3]
	v_pk_fma_f32 v[4:5], v[38:39], v[138:139], v[4:5]
	v_pk_fma_f32 v[6:7], v[52:53], v[140:141], v[6:7]
	v_pk_fma_f32 v[8:9], v[54:55], v[142:143], v[8:9]
	v_pk_fma_f32 v[2:3], v[40:41], v[144:145], v[2:3]
	v_pk_fma_f32 v[4:5], v[42:43], v[146:147], v[4:5]
	v_pk_fma_f32 v[6:7], v[56:57], v[148:149], v[6:7]
	v_pk_fma_f32 v[8:9], v[58:59], v[150:151], v[8:9]
	v_pk_mul_f32 v[10:11], v[2:3], v[160:161]
	v_pk_mul_f32 v[12:13], v[4:5], v[160:161]
	v_exp_f32_e32 v10, v10
	v_exp_f32_e32 v11, v11
	v_exp_f32_e32 v12, v12
	v_exp_f32_e32 v13, v13
	v_pk_add_f32 v[10:11], v[10:11], v[162:163]
	v_pk_add_f32 v[12:13], v[12:13], v[162:163]
	v_rcp_f32_e32 v10, v10
	v_rcp_f32_e32 v11, v11
	v_rcp_f32_e32 v12, v12
	v_rcp_f32_e32 v13, v13
	v_pk_mul_f32 v[10:11], v[2:3], v[10:11]
	v_pk_mul_f32 v[12:13], v[4:5], v[12:13]
	v_pk_mul_f32 v[10:11], v[6:7], v[10:11]
	v_pk_mul_f32 v[12:13], v[8:9], v[12:13]
	v_cvt_pk_bf16_f32 v14, v10, v11
	v_cvt_pk_bf16_f32 v15, v12, v13
	global_store_dwordx2 v28, v[14:15], s[10:11]
	s_add_u32 s10, s10, 0x1600
	s_addc_u32 s11, s11, 0
	s_waitcnt vmcnt(37)
	v_lshlrev_b32_e32 v152, 16, v84
	v_and_b32_e32 v153, 0xffff0000, v84
	v_lshlrev_b32_e32 v154, 16, v85
	v_and_b32_e32 v155, 0xffff0000, v85
	v_lshlrev_b32_e32 v156, 16, v86
	v_and_b32_e32 v157, 0xffff0000, v86
	v_lshlrev_b32_e32 v158, 16, v87
	v_and_b32_e32 v159, 0xffff0000, v87
	global_load_dwordx2 v[84:85], v28, s[8:9] nt
	global_load_dwordx2 v[86:87], v29, s[8:9] nt
	s_add_u32 s8, s8, 0x2c00
	s_addc_u32 s9, s9, 0
	v_pk_fma_f32 v[2:3], v[32:33], v[136:137], v[44:45]
	v_pk_fma_f32 v[4:5], v[34:35], v[138:139], v[46:47]
	v_pk_fma_f32 v[6:7], v[48:49], v[140:141], v[60:61]
	v_pk_fma_f32 v[8:9], v[50:51], v[142:143], v[62:63]
	v_pk_fma_f32 v[2:3], v[36:37], v[144:145], v[2:3]
	v_pk_fma_f32 v[4:5], v[38:39], v[146:147], v[4:5]
	v_pk_fma_f32 v[6:7], v[52:53], v[148:149], v[6:7]
	v_pk_fma_f32 v[8:9], v[54:55], v[150:151], v[8:9]
	v_pk_fma_f32 v[2:3], v[40:41], v[152:153], v[2:3]
	v_pk_fma_f32 v[4:5], v[42:43], v[154:155], v[4:5]
	v_pk_fma_f32 v[6:7], v[56:57], v[156:157], v[6:7]
	v_pk_fma_f32 v[8:9], v[58:59], v[158:159], v[8:9]
	v_pk_mul_f32 v[10:11], v[2:3], v[160:161]
	v_pk_mul_f32 v[12:13], v[4:5], v[160:161]
	v_exp_f32_e32 v10, v10
	v_exp_f32_e32 v11, v11
	v_exp_f32_e32 v12, v12
	v_exp_f32_e32 v13, v13
	v_pk_add_f32 v[10:11], v[10:11], v[162:163]
	v_pk_add_f32 v[12:13], v[12:13], v[162:163]
	v_rcp_f32_e32 v10, v10
	v_rcp_f32_e32 v11, v11
	v_rcp_f32_e32 v12, v12
	v_rcp_f32_e32 v13, v13
	v_pk_mul_f32 v[10:11], v[2:3], v[10:11]
	v_pk_mul_f32 v[12:13], v[4:5], v[12:13]
	v_pk_mul_f32 v[10:11], v[6:7], v[10:11]
	v_pk_mul_f32 v[12:13], v[8:9], v[12:13]
	v_cvt_pk_bf16_f32 v14, v10, v11
	v_cvt_pk_bf16_f32 v15, v12, v13
	global_store_dwordx2 v28, v[14:15], s[10:11]
	s_add_u32 s10, s10, 0x1600
	s_addc_u32 s11, s11, 0
	s_waitcnt vmcnt(38)
	v_lshlrev_b32_e32 v136, 16, v88
	v_and_b32_e32 v137, 0xffff0000, v88
	v_lshlrev_b32_e32 v138, 16, v89
	v_and_b32_e32 v139, 0xffff0000, v89
	v_lshlrev_b32_e32 v140, 16, v90
	v_and_b32_e32 v141, 0xffff0000, v90
	v_lshlrev_b32_e32 v142, 16, v91
	v_and_b32_e32 v143, 0xffff0000, v91
	global_load_dwordx2 v[88:89], v28, s[8:9] nt
	global_load_dwordx2 v[90:91], v29, s[8:9] nt
	s_add_u32 s8, s8, 0x2c00
	s_addc_u32 s9, s9, 0
	v_pk_fma_f32 v[2:3], v[32:33], v[144:145], v[44:45]
	v_pk_fma_f32 v[4:5], v[34:35], v[146:147], v[46:47]
	v_pk_fma_f32 v[6:7], v[48:49], v[148:149], v[60:61]
	v_pk_fma_f32 v[8:9], v[50:51], v[150:151], v[62:63]
	v_pk_fma_f32 v[2:3], v[36:37], v[152:153], v[2:3]
	v_pk_fma_f32 v[4:5], v[38:39], v[154:155], v[4:5]
	v_pk_fma_f32 v[6:7], v[52:53], v[156:157], v[6:7]
	v_pk_fma_f32 v[8:9], v[54:55], v[158:159], v[8:9]
	v_pk_fma_f32 v[2:3], v[40:41], v[136:137], v[2:3]
	v_pk_fma_f32 v[4:5], v[42:43], v[138:139], v[4:5]
	v_pk_fma_f32 v[6:7], v[56:57], v[140:141], v[6:7]
	v_pk_fma_f32 v[8:9], v[58:59], v[142:143], v[8:9]
	v_pk_mul_f32 v[10:11], v[2:3], v[160:161]
	v_pk_mul_f32 v[12:13], v[4:5], v[160:161]
	v_exp_f32_e32 v10, v10
	v_exp_f32_e32 v11, v11
	v_exp_f32_e32 v12, v12
	v_exp_f32_e32 v13, v13
	v_pk_add_f32 v[10:11], v[10:11], v[162:163]
	v_pk_add_f32 v[12:13], v[12:13], v[162:163]
	v_rcp_f32_e32 v10, v10
	v_rcp_f32_e32 v11, v11
	v_rcp_f32_e32 v12, v12
	v_rcp_f32_e32 v13, v13
	v_pk_mul_f32 v[10:11], v[2:3], v[10:11]
	v_pk_mul_f32 v[12:13], v[4:5], v[12:13]
	v_pk_mul_f32 v[10:11], v[6:7], v[10:11]
	v_pk_mul_f32 v[12:13], v[8:9], v[12:13]
	v_cvt_pk_bf16_f32 v14, v10, v11
	v_cvt_pk_bf16_f32 v15, v12, v13
	global_store_dwordx2 v28, v[14:15], s[10:11]
	s_add_u32 s10, s10, 0x1600
	s_addc_u32 s11, s11, 0
	s_waitcnt vmcnt(39)
	v_lshlrev_b32_e32 v144, 16, v92
	v_and_b32_e32 v145, 0xffff0000, v92
	v_lshlrev_b32_e32 v146, 16, v93
	v_and_b32_e32 v147, 0xffff0000, v93
	v_lshlrev_b32_e32 v148, 16, v94
	v_and_b32_e32 v149, 0xffff0000, v94
	v_lshlrev_b32_e32 v150, 16, v95
	v_and_b32_e32 v151, 0xffff0000, v95
	global_load_dwordx2 v[92:93], v28, s[8:9] nt
	global_load_dwordx2 v[94:95], v29, s[8:9] nt
	s_add_u32 s8, s8, 0x2c00
	s_addc_u32 s9, s9, 0
	v_pk_fma_f32 v[2:3], v[32:33], v[152:153], v[44:45]
	v_pk_fma_f32 v[4:5], v[34:35], v[154:155], v[46:47]
	v_pk_fma_f32 v[6:7], v[48:49], v[156:157], v[60:61]
	v_pk_fma_f32 v[8:9], v[50:51], v[158:159], v[62:63]
	v_pk_fma_f32 v[2:3], v[36:37], v[136:137], v[2:3]
	v_pk_fma_f32 v[4:5], v[38:39], v[138:139], v[4:5]
	v_pk_fma_f32 v[6:7], v[52:53], v[140:141], v[6:7]
	v_pk_fma_f32 v[8:9], v[54:55], v[142:143], v[8:9]
	v_pk_fma_f32 v[2:3], v[40:41], v[144:145], v[2:3]
	v_pk_fma_f32 v[4:5], v[42:43], v[146:147], v[4:5]
	v_pk_fma_f32 v[6:7], v[56:57], v[148:149], v[6:7]
	v_pk_fma_f32 v[8:9], v[58:59], v[150:151], v[8:9]
	v_pk_mul_f32 v[10:11], v[2:3], v[160:161]
	v_pk_mul_f32 v[12:13], v[4:5], v[160:161]
	v_exp_f32_e32 v10, v10
	v_exp_f32_e32 v11, v11
	v_exp_f32_e32 v12, v12
	v_exp_f32_e32 v13, v13
	v_pk_add_f32 v[10:11], v[10:11], v[162:163]
	v_pk_add_f32 v[12:13], v[12:13], v[162:163]
	v_rcp_f32_e32 v10, v10
	v_rcp_f32_e32 v11, v11
	v_rcp_f32_e32 v12, v12
	v_rcp_f32_e32 v13, v13
	v_pk_mul_f32 v[10:11], v[2:3], v[10:11]
	v_pk_mul_f32 v[12:13], v[4:5], v[12:13]
	v_pk_mul_f32 v[10:11], v[6:7], v[10:11]
	v_pk_mul_f32 v[12:13], v[8:9], v[12:13]
	v_cvt_pk_bf16_f32 v14, v10, v11
	v_cvt_pk_bf16_f32 v15, v12, v13
	global_store_dwordx2 v28, v[14:15], s[10:11]
	s_add_u32 s10, s10, 0x1600
	s_addc_u32 s11, s11, 0
	s_waitcnt vmcnt(40)
	v_lshlrev_b32_e32 v152, 16, v96
	v_and_b32_e32 v153, 0xffff0000, v96
	v_lshlrev_b32_e32 v154, 16, v97
	v_and_b32_e32 v155, 0xffff0000, v97
	v_lshlrev_b32_e32 v156, 16, v98
	v_and_b32_e32 v157, 0xffff0000, v98
	v_lshlrev_b32_e32 v158, 16, v99
	v_and_b32_e32 v159, 0xffff0000, v99
	global_load_dwordx2 v[96:97], v28, s[8:9] nt
	global_load_dwordx2 v[98:99], v29, s[8:9] nt
	s_add_u32 s8, s8, 0x2c00
	s_addc_u32 s9, s9, 0
	v_pk_fma_f32 v[2:3], v[32:33], v[136:137], v[44:45]
	v_pk_fma_f32 v[4:5], v[34:35], v[138:139], v[46:47]
	v_pk_fma_f32 v[6:7], v[48:49], v[140:141], v[60:61]
	v_pk_fma_f32 v[8:9], v[50:51], v[142:143], v[62:63]
	v_pk_fma_f32 v[2:3], v[36:37], v[144:145], v[2:3]
	v_pk_fma_f32 v[4:5], v[38:39], v[146:147], v[4:5]
	v_pk_fma_f32 v[6:7], v[52:53], v[148:149], v[6:7]
	v_pk_fma_f32 v[8:9], v[54:55], v[150:151], v[8:9]
	v_pk_fma_f32 v[2:3], v[40:41], v[152:153], v[2:3]
	v_pk_fma_f32 v[4:5], v[42:43], v[154:155], v[4:5]
	v_pk_fma_f32 v[6:7], v[56:57], v[156:157], v[6:7]
	v_pk_fma_f32 v[8:9], v[58:59], v[158:159], v[8:9]
	v_pk_mul_f32 v[10:11], v[2:3], v[160:161]
	v_pk_mul_f32 v[12:13], v[4:5], v[160:161]
	v_exp_f32_e32 v10, v10
	v_exp_f32_e32 v11, v11
	v_exp_f32_e32 v12, v12
	v_exp_f32_e32 v13, v13
	v_pk_add_f32 v[10:11], v[10:11], v[162:163]
	v_pk_add_f32 v[12:13], v[12:13], v[162:163]
	v_rcp_f32_e32 v10, v10
	v_rcp_f32_e32 v11, v11
	v_rcp_f32_e32 v12, v12
	v_rcp_f32_e32 v13, v13
	v_pk_mul_f32 v[10:11], v[2:3], v[10:11]
	v_pk_mul_f32 v[12:13], v[4:5], v[12:13]
	v_pk_mul_f32 v[10:11], v[6:7], v[10:11]
	v_pk_mul_f32 v[12:13], v[8:9], v[12:13]
	v_cvt_pk_bf16_f32 v14, v10, v11
	v_cvt_pk_bf16_f32 v15, v12, v13
	global_store_dwordx2 v28, v[14:15], s[10:11]
	s_add_u32 s10, s10, 0x1600
	s_addc_u32 s11, s11, 0
	s_waitcnt vmcnt(41)
	v_lshlrev_b32_e32 v136, 16, v100
	v_and_b32_e32 v137, 0xffff0000, v100
	v_lshlrev_b32_e32 v138, 16, v101
	v_and_b32_e32 v139, 0xffff0000, v101
	v_lshlrev_b32_e32 v140, 16, v102
	v_and_b32_e32 v141, 0xffff0000, v102
	v_lshlrev_b32_e32 v142, 16, v103
	v_and_b32_e32 v143, 0xffff0000, v103
	global_load_dwordx2 v[100:101], v28, s[8:9] nt
	global_load_dwordx2 v[102:103], v29, s[8:9] nt
	s_add_u32 s8, s8, 0x2c00
	s_addc_u32 s9, s9, 0
	v_pk_fma_f32 v[2:3], v[32:33], v[144:145], v[44:45]
	v_pk_fma_f32 v[4:5], v[34:35], v[146:147], v[46:47]
	v_pk_fma_f32 v[6:7], v[48:49], v[148:149], v[60:61]
	v_pk_fma_f32 v[8:9], v[50:51], v[150:151], v[62:63]
	v_pk_fma_f32 v[2:3], v[36:37], v[152:153], v[2:3]
	v_pk_fma_f32 v[4:5], v[38:39], v[154:155], v[4:5]
	v_pk_fma_f32 v[6:7], v[52:53], v[156:157], v[6:7]
	v_pk_fma_f32 v[8:9], v[54:55], v[158:159], v[8:9]
	v_pk_fma_f32 v[2:3], v[40:41], v[136:137], v[2:3]
	v_pk_fma_f32 v[4:5], v[42:43], v[138:139], v[4:5]
	v_pk_fma_f32 v[6:7], v[56:57], v[140:141], v[6:7]
	v_pk_fma_f32 v[8:9], v[58:59], v[142:143], v[8:9]
	v_pk_mul_f32 v[10:11], v[2:3], v[160:161]
	v_pk_mul_f32 v[12:13], v[4:5], v[160:161]
	v_exp_f32_e32 v10, v10
	v_exp_f32_e32 v11, v11
	v_exp_f32_e32 v12, v12
	v_exp_f32_e32 v13, v13
	v_pk_add_f32 v[10:11], v[10:11], v[162:163]
	v_pk_add_f32 v[12:13], v[12:13], v[162:163]
	v_rcp_f32_e32 v10, v10
	v_rcp_f32_e32 v11, v11
	v_rcp_f32_e32 v12, v12
	v_rcp_f32_e32 v13, v13
	v_pk_mul_f32 v[10:11], v[2:3], v[10:11]
	v_pk_mul_f32 v[12:13], v[4:5], v[12:13]
	v_pk_mul_f32 v[10:11], v[6:7], v[10:11]
	v_pk_mul_f32 v[12:13], v[8:9], v[12:13]
	v_cvt_pk_bf16_f32 v14, v10, v11
	v_cvt_pk_bf16_f32 v15, v12, v13
	global_store_dwordx2 v28, v[14:15], s[10:11]
	s_add_u32 s10, s10, 0x1600
	s_addc_u32 s11, s11, 0
	s_waitcnt vmcnt(42)
	v_lshlrev_b32_e32 v144, 16, v104
	v_and_b32_e32 v145, 0xffff0000, v104
	v_lshlrev_b32_e32 v146, 16, v105
	v_and_b32_e32 v147, 0xffff0000, v105
	v_lshlrev_b32_e32 v148, 16, v106
	v_and_b32_e32 v149, 0xffff0000, v106
	v_lshlrev_b32_e32 v150, 16, v107
	v_and_b32_e32 v151, 0xffff0000, v107
	global_load_dwordx2 v[104:105], v28, s[8:9] nt
	global_load_dwordx2 v[106:107], v29, s[8:9] nt
	s_add_u32 s8, s8, 0x2c00
	s_addc_u32 s9, s9, 0
	v_pk_fma_f32 v[2:3], v[32:33], v[152:153], v[44:45]
	v_pk_fma_f32 v[4:5], v[34:35], v[154:155], v[46:47]
	v_pk_fma_f32 v[6:7], v[48:49], v[156:157], v[60:61]
	v_pk_fma_f32 v[8:9], v[50:51], v[158:159], v[62:63]
	v_pk_fma_f32 v[2:3], v[36:37], v[136:137], v[2:3]
	v_pk_fma_f32 v[4:5], v[38:39], v[138:139], v[4:5]
	v_pk_fma_f32 v[6:7], v[52:53], v[140:141], v[6:7]
	v_pk_fma_f32 v[8:9], v[54:55], v[142:143], v[8:9]
	v_pk_fma_f32 v[2:3], v[40:41], v[144:145], v[2:3]
	v_pk_fma_f32 v[4:5], v[42:43], v[146:147], v[4:5]
	v_pk_fma_f32 v[6:7], v[56:57], v[148:149], v[6:7]
	v_pk_fma_f32 v[8:9], v[58:59], v[150:151], v[8:9]
	v_pk_mul_f32 v[10:11], v[2:3], v[160:161]
	v_pk_mul_f32 v[12:13], v[4:5], v[160:161]
	v_exp_f32_e32 v10, v10
	v_exp_f32_e32 v11, v11
	v_exp_f32_e32 v12, v12
	v_exp_f32_e32 v13, v13
	v_pk_add_f32 v[10:11], v[10:11], v[162:163]
	v_pk_add_f32 v[12:13], v[12:13], v[162:163]
	v_rcp_f32_e32 v10, v10
	v_rcp_f32_e32 v11, v11
	v_rcp_f32_e32 v12, v12
	v_rcp_f32_e32 v13, v13
	v_pk_mul_f32 v[10:11], v[2:3], v[10:11]
	v_pk_mul_f32 v[12:13], v[4:5], v[12:13]
	v_pk_mul_f32 v[10:11], v[6:7], v[10:11]
	v_pk_mul_f32 v[12:13], v[8:9], v[12:13]
	v_cvt_pk_bf16_f32 v14, v10, v11
	v_cvt_pk_bf16_f32 v15, v12, v13
	global_store_dwordx2 v28, v[14:15], s[10:11]
	s_add_u32 s10, s10, 0x1600
	s_addc_u32 s11, s11, 0
	s_waitcnt vmcnt(43)
	v_lshlrev_b32_e32 v152, 16, v108
	v_and_b32_e32 v153, 0xffff0000, v108
	v_lshlrev_b32_e32 v154, 16, v109
	v_and_b32_e32 v155, 0xffff0000, v109
	v_lshlrev_b32_e32 v156, 16, v110
	v_and_b32_e32 v157, 0xffff0000, v110
	v_lshlrev_b32_e32 v158, 16, v111
	v_and_b32_e32 v159, 0xffff0000, v111
	global_load_dwordx2 v[108:109], v28, s[8:9] nt
	global_load_dwordx2 v[110:111], v29, s[8:9] nt
	s_add_u32 s8, s8, 0x2c00
	s_addc_u32 s9, s9, 0
	v_pk_fma_f32 v[2:3], v[32:33], v[136:137], v[44:45]
	v_pk_fma_f32 v[4:5], v[34:35], v[138:139], v[46:47]
	v_pk_fma_f32 v[6:7], v[48:49], v[140:141], v[60:61]
	v_pk_fma_f32 v[8:9], v[50:51], v[142:143], v[62:63]
	v_pk_fma_f32 v[2:3], v[36:37], v[144:145], v[2:3]
	v_pk_fma_f32 v[4:5], v[38:39], v[146:147], v[4:5]
	v_pk_fma_f32 v[6:7], v[52:53], v[148:149], v[6:7]
	v_pk_fma_f32 v[8:9], v[54:55], v[150:151], v[8:9]
	v_pk_fma_f32 v[2:3], v[40:41], v[152:153], v[2:3]
	v_pk_fma_f32 v[4:5], v[42:43], v[154:155], v[4:5]
	v_pk_fma_f32 v[6:7], v[56:57], v[156:157], v[6:7]
	v_pk_fma_f32 v[8:9], v[58:59], v[158:159], v[8:9]
	v_pk_mul_f32 v[10:11], v[2:3], v[160:161]
	v_pk_mul_f32 v[12:13], v[4:5], v[160:161]
	v_exp_f32_e32 v10, v10
	v_exp_f32_e32 v11, v11
	v_exp_f32_e32 v12, v12
	v_exp_f32_e32 v13, v13
	v_pk_add_f32 v[10:11], v[10:11], v[162:163]
	v_pk_add_f32 v[12:13], v[12:13], v[162:163]
	v_rcp_f32_e32 v10, v10
	v_rcp_f32_e32 v11, v11
	v_rcp_f32_e32 v12, v12
	v_rcp_f32_e32 v13, v13
	v_pk_mul_f32 v[10:11], v[2:3], v[10:11]
	v_pk_mul_f32 v[12:13], v[4:5], v[12:13]
	v_pk_mul_f32 v[10:11], v[6:7], v[10:11]
	v_pk_mul_f32 v[12:13], v[8:9], v[12:13]
	v_cvt_pk_bf16_f32 v14, v10, v11
	v_cvt_pk_bf16_f32 v15, v12, v13
	global_store_dwordx2 v28, v[14:15], s[10:11]
	s_add_u32 s10, s10, 0x1600
	s_addc_u32 s11, s11, 0
	s_waitcnt vmcnt(44)
	v_lshlrev_b32_e32 v136, 16, v112
	v_and_b32_e32 v137, 0xffff0000, v112
	v_lshlrev_b32_e32 v138, 16, v113
	v_and_b32_e32 v139, 0xffff0000, v113
	v_lshlrev_b32_e32 v140, 16, v114
	v_and_b32_e32 v141, 0xffff0000, v114
	v_lshlrev_b32_e32 v142, 16, v115
	v_and_b32_e32 v143, 0xffff0000, v115
	global_load_dwordx2 v[112:113], v28, s[8:9] nt
	global_load_dwordx2 v[114:115], v29, s[8:9] nt
	s_add_u32 s8, s8, 0x2c00
	s_addc_u32 s9, s9, 0
	v_pk_fma_f32 v[2:3], v[32:33], v[144:145], v[44:45]
	v_pk_fma_f32 v[4:5], v[34:35], v[146:147], v[46:47]
	v_pk_fma_f32 v[6:7], v[48:49], v[148:149], v[60:61]
	v_pk_fma_f32 v[8:9], v[50:51], v[150:151], v[62:63]
	v_pk_fma_f32 v[2:3], v[36:37], v[152:153], v[2:3]
	v_pk_fma_f32 v[4:5], v[38:39], v[154:155], v[4:5]
	v_pk_fma_f32 v[6:7], v[52:53], v[156:157], v[6:7]
	v_pk_fma_f32 v[8:9], v[54:55], v[158:159], v[8:9]
	v_pk_fma_f32 v[2:3], v[40:41], v[136:137], v[2:3]
	v_pk_fma_f32 v[4:5], v[42:43], v[138:139], v[4:5]
	v_pk_fma_f32 v[6:7], v[56:57], v[140:141], v[6:7]
	v_pk_fma_f32 v[8:9], v[58:59], v[142:143], v[8:9]
	v_pk_mul_f32 v[10:11], v[2:3], v[160:161]
	v_pk_mul_f32 v[12:13], v[4:5], v[160:161]
	v_exp_f32_e32 v10, v10
	v_exp_f32_e32 v11, v11
	v_exp_f32_e32 v12, v12
	v_exp_f32_e32 v13, v13
	v_pk_add_f32 v[10:11], v[10:11], v[162:163]
	v_pk_add_f32 v[12:13], v[12:13], v[162:163]
	v_rcp_f32_e32 v10, v10
	v_rcp_f32_e32 v11, v11
	v_rcp_f32_e32 v12, v12
	v_rcp_f32_e32 v13, v13
	v_pk_mul_f32 v[10:11], v[2:3], v[10:11]
	v_pk_mul_f32 v[12:13], v[4:5], v[12:13]
	v_pk_mul_f32 v[10:11], v[6:7], v[10:11]
	v_pk_mul_f32 v[12:13], v[8:9], v[12:13]
	v_cvt_pk_bf16_f32 v14, v10, v11
	v_cvt_pk_bf16_f32 v15, v12, v13
	global_store_dwordx2 v28, v[14:15], s[10:11]
	s_add_u32 s10, s10, 0x1600
	s_addc_u32 s11, s11, 0
	s_waitcnt vmcnt(45)
	v_lshlrev_b32_e32 v144, 16, v116
	v_and_b32_e32 v145, 0xffff0000, v116
	v_lshlrev_b32_e32 v146, 16, v117
	v_and_b32_e32 v147, 0xffff0000, v117
	v_lshlrev_b32_e32 v148, 16, v118
	v_and_b32_e32 v149, 0xffff0000, v118
	v_lshlrev_b32_e32 v150, 16, v119
	v_and_b32_e32 v151, 0xffff0000, v119
	global_load_dwordx2 v[116:117], v28, s[8:9] nt
	global_load_dwordx2 v[118:119], v29, s[8:9] nt
	s_add_u32 s8, s8, 0x2c00
	s_addc_u32 s9, s9, 0
	v_pk_fma_f32 v[2:3], v[32:33], v[152:153], v[44:45]
	v_pk_fma_f32 v[4:5], v[34:35], v[154:155], v[46:47]
	v_pk_fma_f32 v[6:7], v[48:49], v[156:157], v[60:61]
	v_pk_fma_f32 v[8:9], v[50:51], v[158:159], v[62:63]
	v_pk_fma_f32 v[2:3], v[36:37], v[136:137], v[2:3]
	v_pk_fma_f32 v[4:5], v[38:39], v[138:139], v[4:5]
	v_pk_fma_f32 v[6:7], v[52:53], v[140:141], v[6:7]
	v_pk_fma_f32 v[8:9], v[54:55], v[142:143], v[8:9]
	v_pk_fma_f32 v[2:3], v[40:41], v[144:145], v[2:3]
	v_pk_fma_f32 v[4:5], v[42:43], v[146:147], v[4:5]
	v_pk_fma_f32 v[6:7], v[56:57], v[148:149], v[6:7]
	v_pk_fma_f32 v[8:9], v[58:59], v[150:151], v[8:9]
	v_pk_mul_f32 v[10:11], v[2:3], v[160:161]
	v_pk_mul_f32 v[12:13], v[4:5], v[160:161]
	v_exp_f32_e32 v10, v10
	v_exp_f32_e32 v11, v11
	v_exp_f32_e32 v12, v12
	v_exp_f32_e32 v13, v13
	v_pk_add_f32 v[10:11], v[10:11], v[162:163]
	v_pk_add_f32 v[12:13], v[12:13], v[162:163]
	v_rcp_f32_e32 v10, v10
	v_rcp_f32_e32 v11, v11
	v_rcp_f32_e32 v12, v12
	v_rcp_f32_e32 v13, v13
	v_pk_mul_f32 v[10:11], v[2:3], v[10:11]
	v_pk_mul_f32 v[12:13], v[4:5], v[12:13]
	v_pk_mul_f32 v[10:11], v[6:7], v[10:11]
	v_pk_mul_f32 v[12:13], v[8:9], v[12:13]
	v_cvt_pk_bf16_f32 v14, v10, v11
	v_cvt_pk_bf16_f32 v15, v12, v13
	global_store_dwordx2 v28, v[14:15], s[10:11]
	s_add_u32 s10, s10, 0x1600
	s_addc_u32 s11, s11, 0
	s_waitcnt vmcnt(46)
	v_lshlrev_b32_e32 v152, 16, v120
	v_and_b32_e32 v153, 0xffff0000, v120
	v_lshlrev_b32_e32 v154, 16, v121
	v_and_b32_e32 v155, 0xffff0000, v121
	v_lshlrev_b32_e32 v156, 16, v122
	v_and_b32_e32 v157, 0xffff0000, v122
	v_lshlrev_b32_e32 v158, 16, v123
	v_and_b32_e32 v159, 0xffff0000, v123
	global_load_dwordx2 v[120:121], v28, s[8:9] nt
	global_load_dwordx2 v[122:123], v29, s[8:9] nt
	s_add_u32 s8, s8, 0x2c00
	s_addc_u32 s9, s9, 0
	v_pk_fma_f32 v[2:3], v[32:33], v[136:137], v[44:45]
	v_pk_fma_f32 v[4:5], v[34:35], v[138:139], v[46:47]
	v_pk_fma_f32 v[6:7], v[48:49], v[140:141], v[60:61]
	v_pk_fma_f32 v[8:9], v[50:51], v[142:143], v[62:63]
	v_pk_fma_f32 v[2:3], v[36:37], v[144:145], v[2:3]
	v_pk_fma_f32 v[4:5], v[38:39], v[146:147], v[4:5]
	v_pk_fma_f32 v[6:7], v[52:53], v[148:149], v[6:7]
	v_pk_fma_f32 v[8:9], v[54:55], v[150:151], v[8:9]
	v_pk_fma_f32 v[2:3], v[40:41], v[152:153], v[2:3]
	v_pk_fma_f32 v[4:5], v[42:43], v[154:155], v[4:5]
	v_pk_fma_f32 v[6:7], v[56:57], v[156:157], v[6:7]
	v_pk_fma_f32 v[8:9], v[58:59], v[158:159], v[8:9]
	v_pk_mul_f32 v[10:11], v[2:3], v[160:161]
	v_pk_mul_f32 v[12:13], v[4:5], v[160:161]
	v_exp_f32_e32 v10, v10
	v_exp_f32_e32 v11, v11
	v_exp_f32_e32 v12, v12
	v_exp_f32_e32 v13, v13
	v_pk_add_f32 v[10:11], v[10:11], v[162:163]
	v_pk_add_f32 v[12:13], v[12:13], v[162:163]
	v_rcp_f32_e32 v10, v10
	v_rcp_f32_e32 v11, v11
	v_rcp_f32_e32 v12, v12
	v_rcp_f32_e32 v13, v13
	v_pk_mul_f32 v[10:11], v[2:3], v[10:11]
	v_pk_mul_f32 v[12:13], v[4:5], v[12:13]
	v_pk_mul_f32 v[10:11], v[6:7], v[10:11]
	v_pk_mul_f32 v[12:13], v[8:9], v[12:13]
	v_cvt_pk_bf16_f32 v14, v10, v11
	v_cvt_pk_bf16_f32 v15, v12, v13
	global_store_dwordx2 v28, v[14:15], s[10:11]
	s_add_u32 s10, s10, 0x1600
	s_addc_u32 s11, s11, 0
	s_waitcnt vmcnt(47)
	v_lshlrev_b32_e32 v136, 16, v124
	v_and_b32_e32 v137, 0xffff0000, v124
	v_lshlrev_b32_e32 v138, 16, v125
	v_and_b32_e32 v139, 0xffff0000, v125
	v_lshlrev_b32_e32 v140, 16, v126
	v_and_b32_e32 v141, 0xffff0000, v126
	v_lshlrev_b32_e32 v142, 16, v127
	v_and_b32_e32 v143, 0xffff0000, v127
	global_load_dwordx2 v[124:125], v28, s[8:9] nt
	global_load_dwordx2 v[126:127], v29, s[8:9] nt
	s_add_u32 s8, s8, 0x2c00
	s_addc_u32 s9, s9, 0
	v_pk_fma_f32 v[2:3], v[32:33], v[144:145], v[44:45]
	v_pk_fma_f32 v[4:5], v[34:35], v[146:147], v[46:47]
	v_pk_fma_f32 v[6:7], v[48:49], v[148:149], v[60:61]
	v_pk_fma_f32 v[8:9], v[50:51], v[150:151], v[62:63]
	v_pk_fma_f32 v[2:3], v[36:37], v[152:153], v[2:3]
	v_pk_fma_f32 v[4:5], v[38:39], v[154:155], v[4:5]
	v_pk_fma_f32 v[6:7], v[52:53], v[156:157], v[6:7]
	v_pk_fma_f32 v[8:9], v[54:55], v[158:159], v[8:9]
	v_pk_fma_f32 v[2:3], v[40:41], v[136:137], v[2:3]
	v_pk_fma_f32 v[4:5], v[42:43], v[138:139], v[4:5]
	v_pk_fma_f32 v[6:7], v[56:57], v[140:141], v[6:7]
	v_pk_fma_f32 v[8:9], v[58:59], v[142:143], v[8:9]
	v_pk_mul_f32 v[10:11], v[2:3], v[160:161]
	v_pk_mul_f32 v[12:13], v[4:5], v[160:161]
	v_exp_f32_e32 v10, v10
	v_exp_f32_e32 v11, v11
	v_exp_f32_e32 v12, v12
	v_exp_f32_e32 v13, v13
	v_pk_add_f32 v[10:11], v[10:11], v[162:163]
	v_pk_add_f32 v[12:13], v[12:13], v[162:163]
	v_rcp_f32_e32 v10, v10
	v_rcp_f32_e32 v11, v11
	v_rcp_f32_e32 v12, v12
	v_rcp_f32_e32 v13, v13
	v_pk_mul_f32 v[10:11], v[2:3], v[10:11]
	v_pk_mul_f32 v[12:13], v[4:5], v[12:13]
	v_pk_mul_f32 v[10:11], v[6:7], v[10:11]
	v_pk_mul_f32 v[12:13], v[8:9], v[12:13]
	v_cvt_pk_bf16_f32 v14, v10, v11
	v_cvt_pk_bf16_f32 v15, v12, v13
	global_store_dwordx2 v28, v[14:15], s[10:11]
	s_add_u32 s10, s10, 0x1600
	s_addc_u32 s11, s11, 0
	s_waitcnt vmcnt(48)
	v_lshlrev_b32_e32 v144, 16, v128
	v_and_b32_e32 v145, 0xffff0000, v128
	v_lshlrev_b32_e32 v146, 16, v129
	v_and_b32_e32 v147, 0xffff0000, v129
	v_lshlrev_b32_e32 v148, 16, v130
	v_and_b32_e32 v149, 0xffff0000, v130
	v_lshlrev_b32_e32 v150, 16, v131
	v_and_b32_e32 v151, 0xffff0000, v131
	global_load_dwordx2 v[128:129], v28, s[8:9] nt
	global_load_dwordx2 v[130:131], v29, s[8:9] nt
	s_add_u32 s8, s8, 0x2c00
	s_addc_u32 s9, s9, 0
	v_pk_fma_f32 v[2:3], v[32:33], v[152:153], v[44:45]
	v_pk_fma_f32 v[4:5], v[34:35], v[154:155], v[46:47]
	v_pk_fma_f32 v[6:7], v[48:49], v[156:157], v[60:61]
	v_pk_fma_f32 v[8:9], v[50:51], v[158:159], v[62:63]
	v_pk_fma_f32 v[2:3], v[36:37], v[136:137], v[2:3]
	v_pk_fma_f32 v[4:5], v[38:39], v[138:139], v[4:5]
	v_pk_fma_f32 v[6:7], v[52:53], v[140:141], v[6:7]
	v_pk_fma_f32 v[8:9], v[54:55], v[142:143], v[8:9]
	v_pk_fma_f32 v[2:3], v[40:41], v[144:145], v[2:3]
	v_pk_fma_f32 v[4:5], v[42:43], v[146:147], v[4:5]
	v_pk_fma_f32 v[6:7], v[56:57], v[148:149], v[6:7]
	v_pk_fma_f32 v[8:9], v[58:59], v[150:151], v[8:9]
	v_pk_mul_f32 v[10:11], v[2:3], v[160:161]
	v_pk_mul_f32 v[12:13], v[4:5], v[160:161]
	v_exp_f32_e32 v10, v10
	v_exp_f32_e32 v11, v11
	v_exp_f32_e32 v12, v12
	v_exp_f32_e32 v13, v13
	v_pk_add_f32 v[10:11], v[10:11], v[162:163]
	v_pk_add_f32 v[12:13], v[12:13], v[162:163]
	v_rcp_f32_e32 v10, v10
	v_rcp_f32_e32 v11, v11
	v_rcp_f32_e32 v12, v12
	v_rcp_f32_e32 v13, v13
	v_pk_mul_f32 v[10:11], v[2:3], v[10:11]
	v_pk_mul_f32 v[12:13], v[4:5], v[12:13]
	v_pk_mul_f32 v[10:11], v[6:7], v[10:11]
	v_pk_mul_f32 v[12:13], v[8:9], v[12:13]
	v_cvt_pk_bf16_f32 v14, v10, v11
	v_cvt_pk_bf16_f32 v15, v12, v13
	global_store_dwordx2 v28, v[14:15], s[10:11]
	s_add_u32 s10, s10, 0x1600
	s_addc_u32 s11, s11, 0
	s_cmp_eq_u32 s15, 0
	s_cbranch_scc1 .Lffn_nox1
	s_lshr_b32 s0, s13, 7
	s_mul_i32 s0, s0, 0xb000
	s_add_u32 s4, s22, 0x905c000
	s_addc_u32 s5, s23, 0
	s_add_u32 s4, s4, s0
	s_addc_u32 s5, s5, 0
	global_store_dwordx4 v30, v[144:147], s[4:5]
	global_store_dwordx4 v31, v[148:151], s[4:5]
.Lffn_nox1:
	s_waitcnt vmcnt(49)
	v_lshlrev_b32_e32 v152, 16, v132
	v_and_b32_e32 v153, 0xffff0000, v132
	v_lshlrev_b32_e32 v154, 16, v133
	v_and_b32_e32 v155, 0xffff0000, v133
	v_lshlrev_b32_e32 v156, 16, v134
	v_and_b32_e32 v157, 0xffff0000, v134
	v_lshlrev_b32_e32 v158, 16, v135
	v_and_b32_e32 v159, 0xffff0000, v135
	global_load_dwordx2 v[132:133], v28, s[8:9] nt
	global_load_dwordx2 v[134:135], v29, s[8:9] nt
	s_add_u32 s8, s8, 0x2c00
	s_addc_u32 s9, s9, 0
	v_pk_fma_f32 v[2:3], v[32:33], v[136:137], v[44:45]
	v_pk_fma_f32 v[4:5], v[34:35], v[138:139], v[46:47]
	v_pk_fma_f32 v[6:7], v[48:49], v[140:141], v[60:61]
	v_pk_fma_f32 v[8:9], v[50:51], v[142:143], v[62:63]
	v_pk_fma_f32 v[2:3], v[36:37], v[144:145], v[2:3]
	v_pk_fma_f32 v[4:5], v[38:39], v[146:147], v[4:5]
	v_pk_fma_f32 v[6:7], v[52:53], v[148:149], v[6:7]
	v_pk_fma_f32 v[8:9], v[54:55], v[150:151], v[8:9]
	v_pk_fma_f32 v[2:3], v[40:41], v[152:153], v[2:3]
	v_pk_fma_f32 v[4:5], v[42:43], v[154:155], v[4:5]
	v_pk_fma_f32 v[6:7], v[56:57], v[156:157], v[6:7]
	v_pk_fma_f32 v[8:9], v[58:59], v[158:159], v[8:9]
	v_pk_mul_f32 v[10:11], v[2:3], v[160:161]
	v_pk_mul_f32 v[12:13], v[4:5], v[160:161]
	v_exp_f32_e32 v10, v10
	v_exp_f32_e32 v11, v11
	v_exp_f32_e32 v12, v12
	v_exp_f32_e32 v13, v13
	v_pk_add_f32 v[10:11], v[10:11], v[162:163]
	v_pk_add_f32 v[12:13], v[12:13], v[162:163]
	v_rcp_f32_e32 v10, v10
	v_rcp_f32_e32 v11, v11
	v_rcp_f32_e32 v12, v12
	v_rcp_f32_e32 v13, v13
	v_pk_mul_f32 v[10:11], v[2:3], v[10:11]
	v_pk_mul_f32 v[12:13], v[4:5], v[12:13]
	v_pk_mul_f32 v[10:11], v[6:7], v[10:11]
	v_pk_mul_f32 v[12:13], v[8:9], v[12:13]
	v_cvt_pk_bf16_f32 v14, v10, v11
	v_cvt_pk_bf16_f32 v15, v12, v13
	global_store_dwordx2 v28, v[14:15], s[10:11]
	s_add_u32 s10, s10, 0x1600
	s_addc_u32 s11, s11, 0
	s_cmp_eq_u32 s15, 0
	s_cbranch_scc1 .Lffn_nox2
	s_lshr_b32 s0, s13, 7
	s_mul_i32 s0, s0, 0xb000
	s_add_u32 s4, s22, 0x9061800
	s_addc_u32 s5, s23, 0
	s_add_u32 s4, s4, s0
	s_addc_u32 s5, s5, 0
	global_store_dwordx4 v30, v[152:155], s[4:5]
	global_store_dwordx4 v31, v[156:159], s[4:5]
.Lffn_nox2:
	s_add_u32 s8, s8, 0x1fc6800
	s_addc_u32 s9, s9, 0
	s_add_u32 s10, s10, 0xfe6000
	s_addc_u32 s11, s11, 0
	s_add_i32 s13, s13, 0xba
	s_sub_i32 s12, s12, 1
	s_cmp_lg_u32 s12, 0
	s_cbranch_scc1 .Lffn_loop
	s_and_b32 s0, s13, 0x7f
	s_cmp_eq_u32 s0, 0
	s_cselect_b32 s14, 0, -1
	s_cmpk_eq_u32 s0, 0x7f
	s_cselect_b32 s15, 1, 0
	s_waitcnt vmcnt(34)
	v_and_b32_e32 v64, s14, v64
	v_and_b32_e32 v65, s14, v65
	v_and_b32_e32 v66, s14, v66
	v_and_b32_e32 v67, s14, v67
	v_lshlrev_b32_e32 v136, 16, v64
	v_and_b32_e32 v137, 0xffff0000, v64
	v_lshlrev_b32_e32 v138, 16, v65
	v_and_b32_e32 v139, 0xffff0000, v65
	v_lshlrev_b32_e32 v140, 16, v66
	v_and_b32_e32 v141, 0xffff0000, v66
	v_lshlrev_b32_e32 v142, 16, v67
	v_and_b32_e32 v143, 0xffff0000, v67
	s_waitcnt vmcnt(32)
	v_and_b32_e32 v68, s14, v68
	v_and_b32_e32 v69, s14, v69
	v_and_b32_e32 v70, s14, v70
	v_and_b32_e32 v71, s14, v71
	v_lshlrev_b32_e32 v144, 16, v68
	v_and_b32_e32 v145, 0xffff0000, v68
	v_lshlrev_b32_e32 v146, 16, v69
	v_and_b32_e32 v147, 0xffff0000, v69
	v_lshlrev_b32_e32 v148, 16, v70
	v_and_b32_e32 v149, 0xffff0000, v70
	v_lshlrev_b32_e32 v150, 16, v71
	v_and_b32_e32 v151, 0xffff0000, v71
	s_waitcnt vmcnt(30)
	v_lshlrev_b32_e32 v152, 16, v72
	v_and_b32_e32 v153, 0xffff0000, v72
	v_lshlrev_b32_e32 v154, 16, v73
	v_and_b32_e32 v155, 0xffff0000, v73
	v_lshlrev_b32_e32 v156, 16, v74
	v_and_b32_e32 v157, 0xffff0000, v74
	v_lshlrev_b32_e32 v158, 16, v75
	v_and_b32_e32 v159, 0xffff0000, v75
	v_pk_fma_f32 v[2:3], v[32:33], v[136:137], v[44:45]
	v_pk_fma_f32 v[4:5], v[34:35], v[138:139], v[46:47]
	v_pk_fma_f32 v[6:7], v[48:49], v[140:141], v[60:61]
	v_pk_fma_f32 v[8:9], v[50:51], v[142:143], v[62:63]
	v_pk_fma_f32 v[2:3], v[36:37], v[144:145], v[2:3]
	v_pk_fma_f32 v[4:5], v[38:39], v[146:147], v[4:5]
	v_pk_fma_f32 v[6:7], v[52:53], v[148:149], v[6:7]
	v_pk_fma_f32 v[8:9], v[54:55], v[150:151], v[8:9]
	v_pk_fma_f32 v[2:3], v[40:41], v[152:153], v[2:3]
	v_pk_fma_f32 v[4:5], v[42:43], v[154:155], v[4:5]
	v_pk_fma_f32 v[6:7], v[56:57], v[156:157], v[6:7]
	v_pk_fma_f32 v[8:9], v[58:59], v[158:159], v[8:9]
	v_pk_mul_f32 v[10:11], v[2:3], v[160:161]
	v_pk_mul_f32 v[12:13], v[4:5], v[160:161]
	v_exp_f32_e32 v10, v10
	v_exp_f32_e32 v11, v11
	v_exp_f32_e32 v12, v12
	v_exp_f32_e32 v13, v13
	v_pk_add_f32 v[10:11], v[10:11], v[162:163]
	v_pk_add_f32 v[12:13], v[12:13], v[162:163]
	v_rcp_f32_e32 v10, v10
	v_rcp_f32_e32 v11, v11
	v_rcp_f32_e32 v12, v12
	v_rcp_f32_e32 v13, v13
	v_pk_mul_f32 v[10:11], v[2:3], v[10:11]
	v_pk_mul_f32 v[12:13], v[4:5], v[12:13]
	v_pk_mul_f32 v[10:11], v[6:7], v[10:11]
	v_pk_mul_f32 v[12:13], v[8:9], v[12:13]
	v_cvt_pk_bf16_f32 v14, v10, v11
	v_cvt_pk_bf16_f32 v15, v12, v13
	global_store_dwordx2 v28, v[14:15], s[10:11]
	s_add_u32 s10, s10, 0x1600
	s_addc_u32 s11, s11, 0
	s_waitcnt vmcnt(29)
	v_lshlrev_b32_e32 v136, 16, v76
	v_and_b32_e32 v137, 0xffff0000, v76
	v_lshlrev_b32_e32 v138, 16, v77
	v_and_b32_e32 v139, 0xffff0000, v77
	v_lshlrev_b32_e32 v140, 16, v78
	v_and_b32_e32 v141, 0xffff0000, v78
	v_lshlrev_b32_e32 v142, 16, v79
	v_and_b32_e32 v143, 0xffff0000, v79
	v_pk_fma_f32 v[2:3], v[32:33], v[144:145], v[44:45]
	v_pk_fma_f32 v[4:5], v[34:35], v[146:147], v[46:47]
	v_pk_fma_f32 v[6:7], v[48:49], v[148:149], v[60:61]
	v_pk_fma_f32 v[8:9], v[50:51], v[150:151], v[62:63]
	v_pk_fma_f32 v[2:3], v[36:37], v[152:153], v[2:3]
	v_pk_fma_f32 v[4:5], v[38:39], v[154:155], v[4:5]
	v_pk_fma_f32 v[6:7], v[52:53], v[156:157], v[6:7]
	v_pk_fma_f32 v[8:9], v[54:55], v[158:159], v[8:9]
	v_pk_fma_f32 v[2:3], v[40:41], v[136:137], v[2:3]
	v_pk_fma_f32 v[4:5], v[42:43], v[138:139], v[4:5]
	v_pk_fma_f32 v[6:7], v[56:57], v[140:141], v[6:7]
	v_pk_fma_f32 v[8:9], v[58:59], v[142:143], v[8:9]
	v_pk_mul_f32 v[10:11], v[2:3], v[160:161]
	v_pk_mul_f32 v[12:13], v[4:5], v[160:161]
	v_exp_f32_e32 v10, v10
	v_exp_f32_e32 v11, v11
	v_exp_f32_e32 v12, v12
	v_exp_f32_e32 v13, v13
	v_pk_add_f32 v[10:11], v[10:11], v[162:163]
	v_pk_add_f32 v[12:13], v[12:13], v[162:163]
	v_rcp_f32_e32 v10, v10
	v_rcp_f32_e32 v11, v11
	v_rcp_f32_e32 v12, v12
	v_rcp_f32_e32 v13, v13
	v_pk_mul_f32 v[10:11], v[2:3], v[10:11]
	v_pk_mul_f32 v[12:13], v[4:5], v[12:13]
	v_pk_mul_f32 v[10:11], v[6:7], v[10:11]
	v_pk_mul_f32 v[12:13], v[8:9], v[12:13]
	v_cvt_pk_bf16_f32 v14, v10, v11
	v_cvt_pk_bf16_f32 v15, v12, v13
	global_store_dwordx2 v28, v[14:15], s[10:11]
	s_add_u32 s10, s10, 0x1600
	s_addc_u32 s11, s11, 0
	s_waitcnt vmcnt(28)
	v_lshlrev_b32_e32 v144, 16, v80
	v_and_b32_e32 v145, 0xffff0000, v80
	v_lshlrev_b32_e32 v146, 16, v81
	v_and_b32_e32 v147, 0xffff0000, v81
	v_lshlrev_b32_e32 v148, 16, v82
	v_and_b32_e32 v149, 0xffff0000, v82
	v_lshlrev_b32_e32 v150, 16, v83
	v_and_b32_e32 v151, 0xffff0000, v83
	v_pk_fma_f32 v[2:3], v[32:33], v[152:153], v[44:45]
	v_pk_fma_f32 v[4:5], v[34:35], v[154:155], v[46:47]
	v_pk_fma_f32 v[6:7], v[48:49], v[156:157], v[60:61]
	v_pk_fma_f32 v[8:9], v[50:51], v[158:159], v[62:63]
	v_pk_fma_f32 v[2:3], v[36:37], v[136:137], v[2:3]
	v_pk_fma_f32 v[4:5], v[38:39], v[138:139], v[4:5]
	v_pk_fma_f32 v[6:7], v[52:53], v[140:141], v[6:7]
	v_pk_fma_f32 v[8:9], v[54:55], v[142:143], v[8:9]
	v_pk_fma_f32 v[2:3], v[40:41], v[144:145], v[2:3]
	v_pk_fma_f32 v[4:5], v[42:43], v[146:147], v[4:5]
	v_pk_fma_f32 v[6:7], v[56:57], v[148:149], v[6:7]
	v_pk_fma_f32 v[8:9], v[58:59], v[150:151], v[8:9]
	v_pk_mul_f32 v[10:11], v[2:3], v[160:161]
	v_pk_mul_f32 v[12:13], v[4:5], v[160:161]
	v_exp_f32_e32 v10, v10
	v_exp_f32_e32 v11, v11
	v_exp_f32_e32 v12, v12
	v_exp_f32_e32 v13, v13
	v_pk_add_f32 v[10:11], v[10:11], v[162:163]
	v_pk_add_f32 v[12:13], v[12:13], v[162:163]
	v_rcp_f32_e32 v10, v10
	v_rcp_f32_e32 v11, v11
	v_rcp_f32_e32 v12, v12
	v_rcp_f32_e32 v13, v13
	v_pk_mul_f32 v[10:11], v[2:3], v[10:11]
	v_pk_mul_f32 v[12:13], v[4:5], v[12:13]
	v_pk_mul_f32 v[10:11], v[6:7], v[10:11]
	v_pk_mul_f32 v[12:13], v[8:9], v[12:13]
	v_cvt_pk_bf16_f32 v14, v10, v11
	v_cvt_pk_bf16_f32 v15, v12, v13
	global_store_dwordx2 v28, v[14:15], s[10:11]
	s_add_u32 s10, s10, 0x1600
	s_addc_u32 s11, s11, 0
	s_waitcnt vmcnt(27)
	v_lshlrev_b32_e32 v152, 16, v84
	v_and_b32_e32 v153, 0xffff0000, v84
	v_lshlrev_b32_e32 v154, 16, v85
	v_and_b32_e32 v155, 0xffff0000, v85
	v_lshlrev_b32_e32 v156, 16, v86
	v_and_b32_e32 v157, 0xffff0000, v86
	v_lshlrev_b32_e32 v158, 16, v87
	v_and_b32_e32 v159, 0xffff0000, v87
	v_pk_fma_f32 v[2:3], v[32:33], v[136:137], v[44:45]
	v_pk_fma_f32 v[4:5], v[34:35], v[138:139], v[46:47]
	v_pk_fma_f32 v[6:7], v[48:49], v[140:141], v[60:61]
	v_pk_fma_f32 v[8:9], v[50:51], v[142:143], v[62:63]
	v_pk_fma_f32 v[2:3], v[36:37], v[144:145], v[2:3]
	v_pk_fma_f32 v[4:5], v[38:39], v[146:147], v[4:5]
	v_pk_fma_f32 v[6:7], v[52:53], v[148:149], v[6:7]
	v_pk_fma_f32 v[8:9], v[54:55], v[150:151], v[8:9]
	v_pk_fma_f32 v[2:3], v[40:41], v[152:153], v[2:3]
	v_pk_fma_f32 v[4:5], v[42:43], v[154:155], v[4:5]
	v_pk_fma_f32 v[6:7], v[56:57], v[156:157], v[6:7]
	v_pk_fma_f32 v[8:9], v[58:59], v[158:159], v[8:9]
	v_pk_mul_f32 v[10:11], v[2:3], v[160:161]
	v_pk_mul_f32 v[12:13], v[4:5], v[160:161]
	v_exp_f32_e32 v10, v10
	v_exp_f32_e32 v11, v11
	v_exp_f32_e32 v12, v12
	v_exp_f32_e32 v13, v13
	v_pk_add_f32 v[10:11], v[10:11], v[162:163]
	v_pk_add_f32 v[12:13], v[12:13], v[162:163]
	v_rcp_f32_e32 v10, v10
	v_rcp_f32_e32 v11, v11
	v_rcp_f32_e32 v12, v12
	v_rcp_f32_e32 v13, v13
	v_pk_mul_f32 v[10:11], v[2:3], v[10:11]
	v_pk_mul_f32 v[12:13], v[4:5], v[12:13]
	v_pk_mul_f32 v[10:11], v[6:7], v[10:11]
	v_pk_mul_f32 v[12:13], v[8:9], v[12:13]
	v_cvt_pk_bf16_f32 v14, v10, v11
	v_cvt_pk_bf16_f32 v15, v12, v13
	global_store_dwordx2 v28, v[14:15], s[10:11]
	s_add_u32 s10, s10, 0x1600
	s_addc_u32 s11, s11, 0
	s_waitcnt vmcnt(26)
	v_lshlrev_b32_e32 v136, 16, v88
	v_and_b32_e32 v137, 0xffff0000, v88
	v_lshlrev_b32_e32 v138, 16, v89
	v_and_b32_e32 v139, 0xffff0000, v89
	v_lshlrev_b32_e32 v140, 16, v90
	v_and_b32_e32 v141, 0xffff0000, v90
	v_lshlrev_b32_e32 v142, 16, v91
	v_and_b32_e32 v143, 0xffff0000, v91
	v_pk_fma_f32 v[2:3], v[32:33], v[144:145], v[44:45]
	v_pk_fma_f32 v[4:5], v[34:35], v[146:147], v[46:47]
	v_pk_fma_f32 v[6:7], v[48:49], v[148:149], v[60:61]
	v_pk_fma_f32 v[8:9], v[50:51], v[150:151], v[62:63]
	v_pk_fma_f32 v[2:3], v[36:37], v[152:153], v[2:3]
	v_pk_fma_f32 v[4:5], v[38:39], v[154:155], v[4:5]
	v_pk_fma_f32 v[6:7], v[52:53], v[156:157], v[6:7]
	v_pk_fma_f32 v[8:9], v[54:55], v[158:159], v[8:9]
	v_pk_fma_f32 v[2:3], v[40:41], v[136:137], v[2:3]
	v_pk_fma_f32 v[4:5], v[42:43], v[138:139], v[4:5]
	v_pk_fma_f32 v[6:7], v[56:57], v[140:141], v[6:7]
	v_pk_fma_f32 v[8:9], v[58:59], v[142:143], v[8:9]
	v_pk_mul_f32 v[10:11], v[2:3], v[160:161]
	v_pk_mul_f32 v[12:13], v[4:5], v[160:161]
	v_exp_f32_e32 v10, v10
	v_exp_f32_e32 v11, v11
	v_exp_f32_e32 v12, v12
	v_exp_f32_e32 v13, v13
	v_pk_add_f32 v[10:11], v[10:11], v[162:163]
	v_pk_add_f32 v[12:13], v[12:13], v[162:163]
	v_rcp_f32_e32 v10, v10
	v_rcp_f32_e32 v11, v11
	v_rcp_f32_e32 v12, v12
	v_rcp_f32_e32 v13, v13
	v_pk_mul_f32 v[10:11], v[2:3], v[10:11]
	v_pk_mul_f32 v[12:13], v[4:5], v[12:13]
	v_pk_mul_f32 v[10:11], v[6:7], v[10:11]
	v_pk_mul_f32 v[12:13], v[8:9], v[12:13]
	v_cvt_pk_bf16_f32 v14, v10, v11
	v_cvt_pk_bf16_f32 v15, v12, v13
	global_store_dwordx2 v28, v[14:15], s[10:11]
	s_add_u32 s10, s10, 0x1600
	s_addc_u32 s11, s11, 0
	s_waitcnt vmcnt(25)
	v_lshlrev_b32_e32 v144, 16, v92
	v_and_b32_e32 v145, 0xffff0000, v92
	v_lshlrev_b32_e32 v146, 16, v93
	v_and_b32_e32 v147, 0xffff0000, v93
	v_lshlrev_b32_e32 v148, 16, v94
	v_and_b32_e32 v149, 0xffff0000, v94
	v_lshlrev_b32_e32 v150, 16, v95
	v_and_b32_e32 v151, 0xffff0000, v95
	v_pk_fma_f32 v[2:3], v[32:33], v[152:153], v[44:45]
	v_pk_fma_f32 v[4:5], v[34:35], v[154:155], v[46:47]
	v_pk_fma_f32 v[6:7], v[48:49], v[156:157], v[60:61]
	v_pk_fma_f32 v[8:9], v[50:51], v[158:159], v[62:63]
	v_pk_fma_f32 v[2:3], v[36:37], v[136:137], v[2:3]
	v_pk_fma_f32 v[4:5], v[38:39], v[138:139], v[4:5]
	v_pk_fma_f32 v[6:7], v[52:53], v[140:141], v[6:7]
	v_pk_fma_f32 v[8:9], v[54:55], v[142:143], v[8:9]
	v_pk_fma_f32 v[2:3], v[40:41], v[144:145], v[2:3]
	v_pk_fma_f32 v[4:5], v[42:43], v[146:147], v[4:5]
	v_pk_fma_f32 v[6:7], v[56:57], v[148:149], v[6:7]
	v_pk_fma_f32 v[8:9], v[58:59], v[150:151], v[8:9]
	v_pk_mul_f32 v[10:11], v[2:3], v[160:161]
	v_pk_mul_f32 v[12:13], v[4:5], v[160:161]
	v_exp_f32_e32 v10, v10
	v_exp_f32_e32 v11, v11
	v_exp_f32_e32 v12, v12
	v_exp_f32_e32 v13, v13
	v_pk_add_f32 v[10:11], v[10:11], v[162:163]
	v_pk_add_f32 v[12:13], v[12:13], v[162:163]
	v_rcp_f32_e32 v10, v10
	v_rcp_f32_e32 v11, v11
	v_rcp_f32_e32 v12, v12
	v_rcp_f32_e32 v13, v13
	v_pk_mul_f32 v[10:11], v[2:3], v[10:11]
	v_pk_mul_f32 v[12:13], v[4:5], v[12:13]
	v_pk_mul_f32 v[10:11], v[6:7], v[10:11]
	v_pk_mul_f32 v[12:13], v[8:9], v[12:13]
	v_cvt_pk_bf16_f32 v14, v10, v11
	v_cvt_pk_bf16_f32 v15, v12, v13
	global_store_dwordx2 v28, v[14:15], s[10:11]
	s_add_u32 s10, s10, 0x1600
	s_addc_u32 s11, s11, 0
	s_waitcnt vmcnt(24)
	v_lshlrev_b32_e32 v152, 16, v96
	v_and_b32_e32 v153, 0xffff0000, v96
	v_lshlrev_b32_e32 v154, 16, v97
	v_and_b32_e32 v155, 0xffff0000, v97
	v_lshlrev_b32_e32 v156, 16, v98
	v_and_b32_e32 v157, 0xffff0000, v98
	v_lshlrev_b32_e32 v158, 16, v99
	v_and_b32_e32 v159, 0xffff0000, v99
	v_pk_fma_f32 v[2:3], v[32:33], v[136:137], v[44:45]
	v_pk_fma_f32 v[4:5], v[34:35], v[138:139], v[46:47]
	v_pk_fma_f32 v[6:7], v[48:49], v[140:141], v[60:61]
	v_pk_fma_f32 v[8:9], v[50:51], v[142:143], v[62:63]
	v_pk_fma_f32 v[2:3], v[36:37], v[144:145], v[2:3]
	v_pk_fma_f32 v[4:5], v[38:39], v[146:147], v[4:5]
	v_pk_fma_f32 v[6:7], v[52:53], v[148:149], v[6:7]
	v_pk_fma_f32 v[8:9], v[54:55], v[150:151], v[8:9]
	v_pk_fma_f32 v[2:3], v[40:41], v[152:153], v[2:3]
	v_pk_fma_f32 v[4:5], v[42:43], v[154:155], v[4:5]
	v_pk_fma_f32 v[6:7], v[56:57], v[156:157], v[6:7]
	v_pk_fma_f32 v[8:9], v[58:59], v[158:159], v[8:9]
	v_pk_mul_f32 v[10:11], v[2:3], v[160:161]
	v_pk_mul_f32 v[12:13], v[4:5], v[160:161]
	v_exp_f32_e32 v10, v10
	v_exp_f32_e32 v11, v11
	v_exp_f32_e32 v12, v12
	v_exp_f32_e32 v13, v13
	v_pk_add_f32 v[10:11], v[10:11], v[162:163]
	v_pk_add_f32 v[12:13], v[12:13], v[162:163]
	v_rcp_f32_e32 v10, v10
	v_rcp_f32_e32 v11, v11
	v_rcp_f32_e32 v12, v12
	v_rcp_f32_e32 v13, v13
	v_pk_mul_f32 v[10:11], v[2:3], v[10:11]
	v_pk_mul_f32 v[12:13], v[4:5], v[12:13]
	v_pk_mul_f32 v[10:11], v[6:7], v[10:11]
	v_pk_mul_f32 v[12:13], v[8:9], v[12:13]
	v_cvt_pk_bf16_f32 v14, v10, v11
	v_cvt_pk_bf16_f32 v15, v12, v13
	global_store_dwordx2 v28, v[14:15], s[10:11]
	s_add_u32 s10, s10, 0x1600
	s_addc_u32 s11, s11, 0
	s_waitcnt vmcnt(23)
	v_lshlrev_b32_e32 v136, 16, v100
	v_and_b32_e32 v137, 0xffff0000, v100
	v_lshlrev_b32_e32 v138, 16, v101
	v_and_b32_e32 v139, 0xffff0000, v101
	v_lshlrev_b32_e32 v140, 16, v102
	v_and_b32_e32 v141, 0xffff0000, v102
	v_lshlrev_b32_e32 v142, 16, v103
	v_and_b32_e32 v143, 0xffff0000, v103
	v_pk_fma_f32 v[2:3], v[32:33], v[144:145], v[44:45]
	v_pk_fma_f32 v[4:5], v[34:35], v[146:147], v[46:47]
	v_pk_fma_f32 v[6:7], v[48:49], v[148:149], v[60:61]
	v_pk_fma_f32 v[8:9], v[50:51], v[150:151], v[62:63]
	v_pk_fma_f32 v[2:3], v[36:37], v[152:153], v[2:3]
	v_pk_fma_f32 v[4:5], v[38:39], v[154:155], v[4:5]
	v_pk_fma_f32 v[6:7], v[52:53], v[156:157], v[6:7]
	v_pk_fma_f32 v[8:9], v[54:55], v[158:159], v[8:9]
	v_pk_fma_f32 v[2:3], v[40:41], v[136:137], v[2:3]
	v_pk_fma_f32 v[4:5], v[42:43], v[138:139], v[4:5]
	v_pk_fma_f32 v[6:7], v[56:57], v[140:141], v[6:7]
	v_pk_fma_f32 v[8:9], v[58:59], v[142:143], v[8:9]
	v_pk_mul_f32 v[10:11], v[2:3], v[160:161]
	v_pk_mul_f32 v[12:13], v[4:5], v[160:161]
	v_exp_f32_e32 v10, v10
	v_exp_f32_e32 v11, v11
	v_exp_f32_e32 v12, v12
	v_exp_f32_e32 v13, v13
	v_pk_add_f32 v[10:11], v[10:11], v[162:163]
	v_pk_add_f32 v[12:13], v[12:13], v[162:163]
	v_rcp_f32_e32 v10, v10
	v_rcp_f32_e32 v11, v11
	v_rcp_f32_e32 v12, v12
	v_rcp_f32_e32 v13, v13
	v_pk_mul_f32 v[10:11], v[2:3], v[10:11]
	v_pk_mul_f32 v[12:13], v[4:5], v[12:13]
	v_pk_mul_f32 v[10:11], v[6:7], v[10:11]
	v_pk_mul_f32 v[12:13], v[8:9], v[12:13]
	v_cvt_pk_bf16_f32 v14, v10, v11
	v_cvt_pk_bf16_f32 v15, v12, v13
	global_store_dwordx2 v28, v[14:15], s[10:11]
	s_add_u32 s10, s10, 0x1600
	s_addc_u32 s11, s11, 0
	s_waitcnt vmcnt(22)
	v_lshlrev_b32_e32 v144, 16, v104
	v_and_b32_e32 v145, 0xffff0000, v104
	v_lshlrev_b32_e32 v146, 16, v105
	v_and_b32_e32 v147, 0xffff0000, v105
	v_lshlrev_b32_e32 v148, 16, v106
	v_and_b32_e32 v149, 0xffff0000, v106
	v_lshlrev_b32_e32 v150, 16, v107
	v_and_b32_e32 v151, 0xffff0000, v107
	v_pk_fma_f32 v[2:3], v[32:33], v[152:153], v[44:45]
	v_pk_fma_f32 v[4:5], v[34:35], v[154:155], v[46:47]
	v_pk_fma_f32 v[6:7], v[48:49], v[156:157], v[60:61]
	v_pk_fma_f32 v[8:9], v[50:51], v[158:159], v[62:63]
	v_pk_fma_f32 v[2:3], v[36:37], v[136:137], v[2:3]
	v_pk_fma_f32 v[4:5], v[38:39], v[138:139], v[4:5]
	v_pk_fma_f32 v[6:7], v[52:53], v[140:141], v[6:7]
	v_pk_fma_f32 v[8:9], v[54:55], v[142:143], v[8:9]
	v_pk_fma_f32 v[2:3], v[40:41], v[144:145], v[2:3]
	v_pk_fma_f32 v[4:5], v[42:43], v[146:147], v[4:5]
	v_pk_fma_f32 v[6:7], v[56:57], v[148:149], v[6:7]
	v_pk_fma_f32 v[8:9], v[58:59], v[150:151], v[8:9]
	v_pk_mul_f32 v[10:11], v[2:3], v[160:161]
	v_pk_mul_f32 v[12:13], v[4:5], v[160:161]
	v_exp_f32_e32 v10, v10
	v_exp_f32_e32 v11, v11
	v_exp_f32_e32 v12, v12
	v_exp_f32_e32 v13, v13
	v_pk_add_f32 v[10:11], v[10:11], v[162:163]
	v_pk_add_f32 v[12:13], v[12:13], v[162:163]
	v_rcp_f32_e32 v10, v10
	v_rcp_f32_e32 v11, v11
	v_rcp_f32_e32 v12, v12
	v_rcp_f32_e32 v13, v13
	v_pk_mul_f32 v[10:11], v[2:3], v[10:11]
	v_pk_mul_f32 v[12:13], v[4:5], v[12:13]
	v_pk_mul_f32 v[10:11], v[6:7], v[10:11]
	v_pk_mul_f32 v[12:13], v[8:9], v[12:13]
	v_cvt_pk_bf16_f32 v14, v10, v11
	v_cvt_pk_bf16_f32 v15, v12, v13
	global_store_dwordx2 v28, v[14:15], s[10:11]
	s_add_u32 s10, s10, 0x1600
	s_addc_u32 s11, s11, 0
	s_waitcnt vmcnt(21)
	v_lshlrev_b32_e32 v152, 16, v108
	v_and_b32_e32 v153, 0xffff0000, v108
	v_lshlrev_b32_e32 v154, 16, v109
	v_and_b32_e32 v155, 0xffff0000, v109
	v_lshlrev_b32_e32 v156, 16, v110
	v_and_b32_e32 v157, 0xffff0000, v110
	v_lshlrev_b32_e32 v158, 16, v111
	v_and_b32_e32 v159, 0xffff0000, v111
	v_pk_fma_f32 v[2:3], v[32:33], v[136:137], v[44:45]
	v_pk_fma_f32 v[4:5], v[34:35], v[138:139], v[46:47]
	v_pk_fma_f32 v[6:7], v[48:49], v[140:141], v[60:61]
	v_pk_fma_f32 v[8:9], v[50:51], v[142:143], v[62:63]
	v_pk_fma_f32 v[2:3], v[36:37], v[144:145], v[2:3]
	v_pk_fma_f32 v[4:5], v[38:39], v[146:147], v[4:5]
	v_pk_fma_f32 v[6:7], v[52:53], v[148:149], v[6:7]
	v_pk_fma_f32 v[8:9], v[54:55], v[150:151], v[8:9]
	v_pk_fma_f32 v[2:3], v[40:41], v[152:153], v[2:3]
	v_pk_fma_f32 v[4:5], v[42:43], v[154:155], v[4:5]
	v_pk_fma_f32 v[6:7], v[56:57], v[156:157], v[6:7]
	v_pk_fma_f32 v[8:9], v[58:59], v[158:159], v[8:9]
	v_pk_mul_f32 v[10:11], v[2:3], v[160:161]
	v_pk_mul_f32 v[12:13], v[4:5], v[160:161]
	v_exp_f32_e32 v10, v10
	v_exp_f32_e32 v11, v11
	v_exp_f32_e32 v12, v12
	v_exp_f32_e32 v13, v13
	v_pk_add_f32 v[10:11], v[10:11], v[162:163]
	v_pk_add_f32 v[12:13], v[12:13], v[162:163]
	v_rcp_f32_e32 v10, v10
	v_rcp_f32_e32 v11, v11
	v_rcp_f32_e32 v12, v12
	v_rcp_f32_e32 v13, v13
	v_pk_mul_f32 v[10:11], v[2:3], v[10:11]
	v_pk_mul_f32 v[12:13], v[4:5], v[12:13]
	v_pk_mul_f32 v[10:11], v[6:7], v[10:11]
	v_pk_mul_f32 v[12:13], v[8:9], v[12:13]
	v_cvt_pk_bf16_f32 v14, v10, v11
	v_cvt_pk_bf16_f32 v15, v12, v13
	global_store_dwordx2 v28, v[14:15], s[10:11]
	s_add_u32 s10, s10, 0x1600
	s_addc_u32 s11, s11, 0
	s_waitcnt vmcnt(20)
	v_lshlrev_b32_e32 v136, 16, v112
	v_and_b32_e32 v137, 0xffff0000, v112
	v_lshlrev_b32_e32 v138, 16, v113
	v_and_b32_e32 v139, 0xffff0000, v113
	v_lshlrev_b32_e32 v140, 16, v114
	v_and_b32_e32 v141, 0xffff0000, v114
	v_lshlrev_b32_e32 v142, 16, v115
	v_and_b32_e32 v143, 0xffff0000, v115
	v_pk_fma_f32 v[2:3], v[32:33], v[144:145], v[44:45]
	v_pk_fma_f32 v[4:5], v[34:35], v[146:147], v[46:47]
	v_pk_fma_f32 v[6:7], v[48:49], v[148:149], v[60:61]
	v_pk_fma_f32 v[8:9], v[50:51], v[150:151], v[62:63]
	v_pk_fma_f32 v[2:3], v[36:37], v[152:153], v[2:3]
	v_pk_fma_f32 v[4:5], v[38:39], v[154:155], v[4:5]
	v_pk_fma_f32 v[6:7], v[52:53], v[156:157], v[6:7]
	v_pk_fma_f32 v[8:9], v[54:55], v[158:159], v[8:9]
	v_pk_fma_f32 v[2:3], v[40:41], v[136:137], v[2:3]
	v_pk_fma_f32 v[4:5], v[42:43], v[138:139], v[4:5]
	v_pk_fma_f32 v[6:7], v[56:57], v[140:141], v[6:7]
	v_pk_fma_f32 v[8:9], v[58:59], v[142:143], v[8:9]
	v_pk_mul_f32 v[10:11], v[2:3], v[160:161]
	v_pk_mul_f32 v[12:13], v[4:5], v[160:161]
	v_exp_f32_e32 v10, v10
	v_exp_f32_e32 v11, v11
	v_exp_f32_e32 v12, v12
	v_exp_f32_e32 v13, v13
	v_pk_add_f32 v[10:11], v[10:11], v[162:163]
	v_pk_add_f32 v[12:13], v[12:13], v[162:163]
	v_rcp_f32_e32 v10, v10
	v_rcp_f32_e32 v11, v11
	v_rcp_f32_e32 v12, v12
	v_rcp_f32_e32 v13, v13
	v_pk_mul_f32 v[10:11], v[2:3], v[10:11]
	v_pk_mul_f32 v[12:13], v[4:5], v[12:13]
	v_pk_mul_f32 v[10:11], v[6:7], v[10:11]
	v_pk_mul_f32 v[12:13], v[8:9], v[12:13]
	v_cvt_pk_bf16_f32 v14, v10, v11
	v_cvt_pk_bf16_f32 v15, v12, v13
	global_store_dwordx2 v28, v[14:15], s[10:11]
	s_add_u32 s10, s10, 0x1600
	s_addc_u32 s11, s11, 0
	s_waitcnt vmcnt(19)
	v_lshlrev_b32_e32 v144, 16, v116
	v_and_b32_e32 v145, 0xffff0000, v116
	v_lshlrev_b32_e32 v146, 16, v117
	v_and_b32_e32 v147, 0xffff0000, v117
	v_lshlrev_b32_e32 v148, 16, v118
	v_and_b32_e32 v149, 0xffff0000, v118
	v_lshlrev_b32_e32 v150, 16, v119
	v_and_b32_e32 v151, 0xffff0000, v119
	v_pk_fma_f32 v[2:3], v[32:33], v[152:153], v[44:45]
	v_pk_fma_f32 v[4:5], v[34:35], v[154:155], v[46:47]
	v_pk_fma_f32 v[6:7], v[48:49], v[156:157], v[60:61]
	v_pk_fma_f32 v[8:9], v[50:51], v[158:159], v[62:63]
	v_pk_fma_f32 v[2:3], v[36:37], v[136:137], v[2:3]
	v_pk_fma_f32 v[4:5], v[38:39], v[138:139], v[4:5]
	v_pk_fma_f32 v[6:7], v[52:53], v[140:141], v[6:7]
	v_pk_fma_f32 v[8:9], v[54:55], v[142:143], v[8:9]
	v_pk_fma_f32 v[2:3], v[40:41], v[144:145], v[2:3]
	v_pk_fma_f32 v[4:5], v[42:43], v[146:147], v[4:5]
	v_pk_fma_f32 v[6:7], v[56:57], v[148:149], v[6:7]
	v_pk_fma_f32 v[8:9], v[58:59], v[150:151], v[8:9]
	v_pk_mul_f32 v[10:11], v[2:3], v[160:161]
	v_pk_mul_f32 v[12:13], v[4:5], v[160:161]
	v_exp_f32_e32 v10, v10
	v_exp_f32_e32 v11, v11
	v_exp_f32_e32 v12, v12
	v_exp_f32_e32 v13, v13
	v_pk_add_f32 v[10:11], v[10:11], v[162:163]
	v_pk_add_f32 v[12:13], v[12:13], v[162:163]
	v_rcp_f32_e32 v10, v10
	v_rcp_f32_e32 v11, v11
	v_rcp_f32_e32 v12, v12
	v_rcp_f32_e32 v13, v13
	v_pk_mul_f32 v[10:11], v[2:3], v[10:11]
	v_pk_mul_f32 v[12:13], v[4:5], v[12:13]
	v_pk_mul_f32 v[10:11], v[6:7], v[10:11]
	v_pk_mul_f32 v[12:13], v[8:9], v[12:13]
	v_cvt_pk_bf16_f32 v14, v10, v11
	v_cvt_pk_bf16_f32 v15, v12, v13
	global_store_dwordx2 v28, v[14:15], s[10:11]
	s_add_u32 s10, s10, 0x1600
	s_addc_u32 s11, s11, 0
	s_waitcnt vmcnt(18)
	v_lshlrev_b32_e32 v152, 16, v120
	v_and_b32_e32 v153, 0xffff0000, v120
	v_lshlrev_b32_e32 v154, 16, v121
	v_and_b32_e32 v155, 0xffff0000, v121
	v_lshlrev_b32_e32 v156, 16, v122
	v_and_b32_e32 v157, 0xffff0000, v122
	v_lshlrev_b32_e32 v158, 16, v123
	v_and_b32_e32 v159, 0xffff0000, v123
	v_pk_fma_f32 v[2:3], v[32:33], v[136:137], v[44:45]
	v_pk_fma_f32 v[4:5], v[34:35], v[138:139], v[46:47]
	v_pk_fma_f32 v[6:7], v[48:49], v[140:141], v[60:61]
	v_pk_fma_f32 v[8:9], v[50:51], v[142:143], v[62:63]
	v_pk_fma_f32 v[2:3], v[36:37], v[144:145], v[2:3]
	v_pk_fma_f32 v[4:5], v[38:39], v[146:147], v[4:5]
	v_pk_fma_f32 v[6:7], v[52:53], v[148:149], v[6:7]
	v_pk_fma_f32 v[8:9], v[54:55], v[150:151], v[8:9]
	v_pk_fma_f32 v[2:3], v[40:41], v[152:153], v[2:3]
	v_pk_fma_f32 v[4:5], v[42:43], v[154:155], v[4:5]
	v_pk_fma_f32 v[6:7], v[56:57], v[156:157], v[6:7]
	v_pk_fma_f32 v[8:9], v[58:59], v[158:159], v[8:9]
	v_pk_mul_f32 v[10:11], v[2:3], v[160:161]
	v_pk_mul_f32 v[12:13], v[4:5], v[160:161]
	v_exp_f32_e32 v10, v10
	v_exp_f32_e32 v11, v11
	v_exp_f32_e32 v12, v12
	v_exp_f32_e32 v13, v13
	v_pk_add_f32 v[10:11], v[10:11], v[162:163]
	v_pk_add_f32 v[12:13], v[12:13], v[162:163]
	v_rcp_f32_e32 v10, v10
	v_rcp_f32_e32 v11, v11
	v_rcp_f32_e32 v12, v12
	v_rcp_f32_e32 v13, v13
	v_pk_mul_f32 v[10:11], v[2:3], v[10:11]
	v_pk_mul_f32 v[12:13], v[4:5], v[12:13]
	v_pk_mul_f32 v[10:11], v[6:7], v[10:11]
	v_pk_mul_f32 v[12:13], v[8:9], v[12:13]
	v_cvt_pk_bf16_f32 v14, v10, v11
	v_cvt_pk_bf16_f32 v15, v12, v13
	global_store_dwordx2 v28, v[14:15], s[10:11]
	s_add_u32 s10, s10, 0x1600
	s_addc_u32 s11, s11, 0
	s_waitcnt vmcnt(17)
	v_lshlrev_b32_e32 v136, 16, v124
	v_and_b32_e32 v137, 0xffff0000, v124
	v_lshlrev_b32_e32 v138, 16, v125
	v_and_b32_e32 v139, 0xffff0000, v125
	v_lshlrev_b32_e32 v140, 16, v126
	v_and_b32_e32 v141, 0xffff0000, v126
	v_lshlrev_b32_e32 v142, 16, v127
	v_and_b32_e32 v143, 0xffff0000, v127
	v_pk_fma_f32 v[2:3], v[32:33], v[144:145], v[44:45]
	v_pk_fma_f32 v[4:5], v[34:35], v[146:147], v[46:47]
	v_pk_fma_f32 v[6:7], v[48:49], v[148:149], v[60:61]
	v_pk_fma_f32 v[8:9], v[50:51], v[150:151], v[62:63]
	v_pk_fma_f32 v[2:3], v[36:37], v[152:153], v[2:3]
	v_pk_fma_f32 v[4:5], v[38:39], v[154:155], v[4:5]
	v_pk_fma_f32 v[6:7], v[52:53], v[156:157], v[6:7]
	v_pk_fma_f32 v[8:9], v[54:55], v[158:159], v[8:9]
	v_pk_fma_f32 v[2:3], v[40:41], v[136:137], v[2:3]
	v_pk_fma_f32 v[4:5], v[42:43], v[138:139], v[4:5]
	v_pk_fma_f32 v[6:7], v[56:57], v[140:141], v[6:7]
	v_pk_fma_f32 v[8:9], v[58:59], v[142:143], v[8:9]
	v_pk_mul_f32 v[10:11], v[2:3], v[160:161]
	v_pk_mul_f32 v[12:13], v[4:5], v[160:161]
	v_exp_f32_e32 v10, v10
	v_exp_f32_e32 v11, v11
	v_exp_f32_e32 v12, v12
	v_exp_f32_e32 v13, v13
	v_pk_add_f32 v[10:11], v[10:11], v[162:163]
	v_pk_add_f32 v[12:13], v[12:13], v[162:163]
	v_rcp_f32_e32 v10, v10
	v_rcp_f32_e32 v11, v11
	v_rcp_f32_e32 v12, v12
	v_rcp_f32_e32 v13, v13
	v_pk_mul_f32 v[10:11], v[2:3], v[10:11]
	v_pk_mul_f32 v[12:13], v[4:5], v[12:13]
	v_pk_mul_f32 v[10:11], v[6:7], v[10:11]
	v_pk_mul_f32 v[12:13], v[8:9], v[12:13]
	v_cvt_pk_bf16_f32 v14, v10, v11
	v_cvt_pk_bf16_f32 v15, v12, v13
	global_store_dwordx2 v28, v[14:15], s[10:11]
	s_add_u32 s10, s10, 0x1600
	s_addc_u32 s11, s11, 0
	s_waitcnt vmcnt(16)
	v_lshlrev_b32_e32 v144, 16, v128
	v_and_b32_e32 v145, 0xffff0000, v128
	v_lshlrev_b32_e32 v146, 16, v129
	v_and_b32_e32 v147, 0xffff0000, v129
	v_lshlrev_b32_e32 v148, 16, v130
	v_and_b32_e32 v149, 0xffff0000, v130
	v_lshlrev_b32_e32 v150, 16, v131
	v_and_b32_e32 v151, 0xffff0000, v131
	v_pk_fma_f32 v[2:3], v[32:33], v[152:153], v[44:45]
	v_pk_fma_f32 v[4:5], v[34:35], v[154:155], v[46:47]
	v_pk_fma_f32 v[6:7], v[48:49], v[156:157], v[60:61]
	v_pk_fma_f32 v[8:9], v[50:51], v[158:159], v[62:63]
	v_pk_fma_f32 v[2:3], v[36:37], v[136:137], v[2:3]
	v_pk_fma_f32 v[4:5], v[38:39], v[138:139], v[4:5]
	v_pk_fma_f32 v[6:7], v[52:53], v[140:141], v[6:7]
	v_pk_fma_f32 v[8:9], v[54:55], v[142:143], v[8:9]
	v_pk_fma_f32 v[2:3], v[40:41], v[144:145], v[2:3]
	v_pk_fma_f32 v[4:5], v[42:43], v[146:147], v[4:5]
	v_pk_fma_f32 v[6:7], v[56:57], v[148:149], v[6:7]
	v_pk_fma_f32 v[8:9], v[58:59], v[150:151], v[8:9]
	v_pk_mul_f32 v[10:11], v[2:3], v[160:161]
	v_pk_mul_f32 v[12:13], v[4:5], v[160:161]
	v_exp_f32_e32 v10, v10
	v_exp_f32_e32 v11, v11
	v_exp_f32_e32 v12, v12
	v_exp_f32_e32 v13, v13
	v_pk_add_f32 v[10:11], v[10:11], v[162:163]
	v_pk_add_f32 v[12:13], v[12:13], v[162:163]
	v_rcp_f32_e32 v10, v10
	v_rcp_f32_e32 v11, v11
	v_rcp_f32_e32 v12, v12
	v_rcp_f32_e32 v13, v13
	v_pk_mul_f32 v[10:11], v[2:3], v[10:11]
	v_pk_mul_f32 v[12:13], v[4:5], v[12:13]
	v_pk_mul_f32 v[10:11], v[6:7], v[10:11]
	v_pk_mul_f32 v[12:13], v[8:9], v[12:13]
	v_cvt_pk_bf16_f32 v14, v10, v11
	v_cvt_pk_bf16_f32 v15, v12, v13
	global_store_dwordx2 v28, v[14:15], s[10:11]
	s_add_u32 s10, s10, 0x1600
	s_addc_u32 s11, s11, 0
	s_cmp_eq_u32 s15, 0
	s_cbranch_scc1 .Lffn_nox3
	s_lshr_b32 s0, s13, 7
	s_mul_i32 s0, s0, 0xb000
	s_add_u32 s4, s22, 0x905c000
	s_addc_u32 s5, s23, 0
	s_add_u32 s4, s4, s0
	s_addc_u32 s5, s5, 0
	global_store_dwordx4 v30, v[144:147], s[4:5]
	global_store_dwordx4 v31, v[148:151], s[4:5]
.Lffn_nox3:
	s_waitcnt vmcnt(15)
	v_lshlrev_b32_e32 v152, 16, v132
	v_and_b32_e32 v153, 0xffff0000, v132
	v_lshlrev_b32_e32 v154, 16, v133
	v_and_b32_e32 v155, 0xffff0000, v133
	v_lshlrev_b32_e32 v156, 16, v134
	v_and_b32_e32 v157, 0xffff0000, v134
	v_lshlrev_b32_e32 v158, 16, v135
	v_and_b32_e32 v159, 0xffff0000, v135
	v_pk_fma_f32 v[2:3], v[32:33], v[136:137], v[44:45]
	v_pk_fma_f32 v[4:5], v[34:35], v[138:139], v[46:47]
	v_pk_fma_f32 v[6:7], v[48:49], v[140:141], v[60:61]
	v_pk_fma_f32 v[8:9], v[50:51], v[142:143], v[62:63]
	v_pk_fma_f32 v[2:3], v[36:37], v[144:145], v[2:3]
	v_pk_fma_f32 v[4:5], v[38:39], v[146:147], v[4:5]
	v_pk_fma_f32 v[6:7], v[52:53], v[148:149], v[6:7]
	v_pk_fma_f32 v[8:9], v[54:55], v[150:151], v[8:9]
	v_pk_fma_f32 v[2:3], v[40:41], v[152:153], v[2:3]
	v_pk_fma_f32 v[4:5], v[42:43], v[154:155], v[4:5]
	v_pk_fma_f32 v[6:7], v[56:57], v[156:157], v[6:7]
	v_pk_fma_f32 v[8:9], v[58:59], v[158:159], v[8:9]
	v_pk_mul_f32 v[10:11], v[2:3], v[160:161]
	v_pk_mul_f32 v[12:13], v[4:5], v[160:161]
	v_exp_f32_e32 v10, v10
	v_exp_f32_e32 v11, v11
	v_exp_f32_e32 v12, v12
	v_exp_f32_e32 v13, v13
	v_pk_add_f32 v[10:11], v[10:11], v[162:163]
	v_pk_add_f32 v[12:13], v[12:13], v[162:163]
	v_rcp_f32_e32 v10, v10
	v_rcp_f32_e32 v11, v11
	v_rcp_f32_e32 v12, v12
	v_rcp_f32_e32 v13, v13
	v_pk_mul_f32 v[10:11], v[2:3], v[10:11]
	v_pk_mul_f32 v[12:13], v[4:5], v[12:13]
	v_pk_mul_f32 v[10:11], v[6:7], v[10:11]
	v_pk_mul_f32 v[12:13], v[8:9], v[12:13]
	v_cvt_pk_bf16_f32 v14, v10, v11
	v_cvt_pk_bf16_f32 v15, v12, v13
	global_store_dwordx2 v28, v[14:15], s[10:11]
	s_add_u32 s10, s10, 0x1600
	s_addc_u32 s11, s11, 0
	s_cmp_eq_u32 s15, 0
	s_cbranch_scc1 .Lffn_nox4
	s_lshr_b32 s0, s13, 7
	s_mul_i32 s0, s0, 0xb000
	s_add_u32 s4, s22, 0x9061800
	s_addc_u32 s5, s23, 0
	s_add_u32 s4, s4, s0
	s_addc_u32 s5, s5, 0
	global_store_dwordx4 v30, v[152:155], s[4:5]
	global_store_dwordx4 v31, v[156:159], s[4:5]
.Lffn_nox4:
	s_cmp_eq_u32 s36, 0
	s_cbranch_scc1 .Lffn_done
	s_waitcnt vmcnt(16)
	v_mov_b32_e32 v136, v178
	v_mov_b32_e32 v140, v182
	v_mov_b32_e32 v144, v186
	v_mov_b32_e32 v148, v190
	v_mov_b32_e32 v137, v179
	v_mov_b32_e32 v141, v183
	v_mov_b32_e32 v145, v187
	v_mov_b32_e32 v149, v191
	v_mov_b32_e32 v138, v180
	v_mov_b32_e32 v142, v184
	v_mov_b32_e32 v146, v188
	v_mov_b32_e32 v150, v192
	v_mov_b32_e32 v139, v181
	v_mov_b32_e32 v143, v185
	v_mov_b32_e32 v147, v189
	v_mov_b32_e32 v151, v193
	s_add_u32 s10, s30, 0x14988000
	s_addc_u32 s11, s31, 0
	s_add_u32 s10, s10, 0x5800000
	s_addc_u32 s11, s11, 0
	s_mul_i32 s0, s37, 0x5800
	s_add_u32 s10, s10, s0
	s_addc_u32 s11, s11, 0
	s_mul_i32 s0, s37, 0xb000
	s_add_u32 s4, s22, 0x90b4000
	s_addc_u32 s5, s23, 0
	s_add_u32 s4, s4, s0
	s_addc_u32 s5, s5, 0
	v_lshlrev_b32_e32 v152, 16, v194
	v_and_b32_e32 v153, 0xffff0000, v194
	v_lshlrev_b32_e32 v154, 16, v195
	v_and_b32_e32 v155, 0xffff0000, v195
	v_lshlrev_b32_e32 v156, 16, v196
	v_and_b32_e32 v157, 0xffff0000, v196
	v_lshlrev_b32_e32 v158, 16, v197
	v_and_b32_e32 v159, 0xffff0000, v197
	v_pk_fma_f32 v[2:3], v[32:33], v[136:137], v[44:45]
	v_pk_fma_f32 v[4:5], v[34:35], v[138:139], v[46:47]
	v_pk_fma_f32 v[6:7], v[48:49], v[140:141], v[60:61]
	v_pk_fma_f32 v[8:9], v[50:51], v[142:143], v[62:63]
	v_pk_fma_f32 v[2:3], v[36:37], v[144:145], v[2:3]
	v_pk_fma_f32 v[4:5], v[38:39], v[146:147], v[4:5]
	v_pk_fma_f32 v[6:7], v[52:53], v[148:149], v[6:7]
	v_pk_fma_f32 v[8:9], v[54:55], v[150:151], v[8:9]
	v_pk_fma_f32 v[2:3], v[40:41], v[152:153], v[2:3]
	v_pk_fma_f32 v[4:5], v[42:43], v[154:155], v[4:5]
	v_pk_fma_f32 v[6:7], v[56:57], v[156:157], v[6:7]
	v_pk_fma_f32 v[8:9], v[58:59], v[158:159], v[8:9]
	v_pk_mul_f32 v[10:11], v[2:3], v[160:161]
	v_pk_mul_f32 v[12:13], v[4:5], v[160:161]
	v_exp_f32_e32 v10, v10
	v_exp_f32_e32 v11, v11
	v_exp_f32_e32 v12, v12
	v_exp_f32_e32 v13, v13
	v_pk_add_f32 v[10:11], v[10:11], v[162:163]
	v_pk_add_f32 v[12:13], v[12:13], v[162:163]
	v_rcp_f32_e32 v10, v10
	v_rcp_f32_e32 v11, v11
	v_rcp_f32_e32 v12, v12
	v_rcp_f32_e32 v13, v13
	v_pk_mul_f32 v[10:11], v[2:3], v[10:11]
	v_pk_mul_f32 v[12:13], v[4:5], v[12:13]
	v_pk_mul_f32 v[10:11], v[6:7], v[10:11]
	v_pk_mul_f32 v[12:13], v[8:9], v[12:13]
	v_cvt_pk_bf16_f32 v14, v10, v11
	v_cvt_pk_bf16_f32 v15, v12, v13
	global_store_dwordx2 v28, v[14:15], s[10:11]
	s_add_u32 s10, s10, 0x1600
	s_addc_u32 s11, s11, 0
	v_lshlrev_b32_e32 v136, 16, v198
	v_and_b32_e32 v137, 0xffff0000, v198
	v_lshlrev_b32_e32 v138, 16, v199
	v_and_b32_e32 v139, 0xffff0000, v199
	v_lshlrev_b32_e32 v140, 16, v200
	v_and_b32_e32 v141, 0xffff0000, v200
	v_lshlrev_b32_e32 v142, 16, v201
	v_and_b32_e32 v143, 0xffff0000, v201
	v_pk_fma_f32 v[2:3], v[32:33], v[144:145], v[44:45]
	v_pk_fma_f32 v[4:5], v[34:35], v[146:147], v[46:47]
	v_pk_fma_f32 v[6:7], v[48:49], v[148:149], v[60:61]
	v_pk_fma_f32 v[8:9], v[50:51], v[150:151], v[62:63]
	v_pk_fma_f32 v[2:3], v[36:37], v[152:153], v[2:3]
	v_pk_fma_f32 v[4:5], v[38:39], v[154:155], v[4:5]
	v_pk_fma_f32 v[6:7], v[52:53], v[156:157], v[6:7]
	v_pk_fma_f32 v[8:9], v[54:55], v[158:159], v[8:9]
	v_pk_fma_f32 v[2:3], v[40:41], v[136:137], v[2:3]
	v_pk_fma_f32 v[4:5], v[42:43], v[138:139], v[4:5]
	v_pk_fma_f32 v[6:7], v[56:57], v[140:141], v[6:7]
	v_pk_fma_f32 v[8:9], v[58:59], v[142:143], v[8:9]
	v_pk_mul_f32 v[10:11], v[2:3], v[160:161]
	v_pk_mul_f32 v[12:13], v[4:5], v[160:161]
	v_exp_f32_e32 v10, v10
	v_exp_f32_e32 v11, v11
	v_exp_f32_e32 v12, v12
	v_exp_f32_e32 v13, v13
	v_pk_add_f32 v[10:11], v[10:11], v[162:163]
	v_pk_add_f32 v[12:13], v[12:13], v[162:163]
	v_rcp_f32_e32 v10, v10
	v_rcp_f32_e32 v11, v11
	v_rcp_f32_e32 v12, v12
	v_rcp_f32_e32 v13, v13
	v_pk_mul_f32 v[10:11], v[2:3], v[10:11]
	v_pk_mul_f32 v[12:13], v[4:5], v[12:13]
	v_pk_mul_f32 v[10:11], v[6:7], v[10:11]
	v_pk_mul_f32 v[12:13], v[8:9], v[12:13]
	v_cvt_pk_bf16_f32 v14, v10, v11
	v_cvt_pk_bf16_f32 v15, v12, v13
	global_store_dwordx2 v28, v[14:15], s[10:11]
	s_add_u32 s10, s10, 0x1600
	s_addc_u32 s11, s11, 0
	v_lshlrev_b32_e32 v144, 16, v202
	v_and_b32_e32 v145, 0xffff0000, v202
	v_lshlrev_b32_e32 v146, 16, v203
	v_and_b32_e32 v147, 0xffff0000, v203
	v_lshlrev_b32_e32 v148, 16, v204
	v_and_b32_e32 v149, 0xffff0000, v204
	v_lshlrev_b32_e32 v150, 16, v205
	v_and_b32_e32 v151, 0xffff0000, v205
	v_pk_fma_f32 v[2:3], v[32:33], v[152:153], v[44:45]
	v_pk_fma_f32 v[4:5], v[34:35], v[154:155], v[46:47]
	v_pk_fma_f32 v[6:7], v[48:49], v[156:157], v[60:61]
	v_pk_fma_f32 v[8:9], v[50:51], v[158:159], v[62:63]
	v_pk_fma_f32 v[2:3], v[36:37], v[136:137], v[2:3]
	v_pk_fma_f32 v[4:5], v[38:39], v[138:139], v[4:5]
	v_pk_fma_f32 v[6:7], v[52:53], v[140:141], v[6:7]
	v_pk_fma_f32 v[8:9], v[54:55], v[142:143], v[8:9]
	v_pk_fma_f32 v[2:3], v[40:41], v[144:145], v[2:3]
	v_pk_fma_f32 v[4:5], v[42:43], v[146:147], v[4:5]
	v_pk_fma_f32 v[6:7], v[56:57], v[148:149], v[6:7]
	v_pk_fma_f32 v[8:9], v[58:59], v[150:151], v[8:9]
	v_pk_mul_f32 v[10:11], v[2:3], v[160:161]
	v_pk_mul_f32 v[12:13], v[4:5], v[160:161]
	v_exp_f32_e32 v10, v10
	v_exp_f32_e32 v11, v11
	v_exp_f32_e32 v12, v12
	v_exp_f32_e32 v13, v13
	v_pk_add_f32 v[10:11], v[10:11], v[162:163]
	v_pk_add_f32 v[12:13], v[12:13], v[162:163]
	v_rcp_f32_e32 v10, v10
	v_rcp_f32_e32 v11, v11
	v_rcp_f32_e32 v12, v12
	v_rcp_f32_e32 v13, v13
	v_pk_mul_f32 v[10:11], v[2:3], v[10:11]
	v_pk_mul_f32 v[12:13], v[4:5], v[12:13]
	v_pk_mul_f32 v[10:11], v[6:7], v[10:11]
	v_pk_mul_f32 v[12:13], v[8:9], v[12:13]
	v_cvt_pk_bf16_f32 v14, v10, v11
	v_cvt_pk_bf16_f32 v15, v12, v13
	global_store_dwordx2 v28, v[14:15], s[10:11]
	s_add_u32 s10, s10, 0x1600
	s_addc_u32 s11, s11, 0
	global_store_dwordx4 v30, v[144:147], s[4:5]
	global_store_dwordx4 v31, v[148:151], s[4:5]
	s_add_u32 s4, s4, 0x5800
	s_addc_u32 s5, s5, 0
	v_lshlrev_b32_e32 v152, 16, v206
	v_and_b32_e32 v153, 0xffff0000, v206
	v_lshlrev_b32_e32 v154, 16, v207
	v_and_b32_e32 v155, 0xffff0000, v207
	v_lshlrev_b32_e32 v156, 16, v208
	v_and_b32_e32 v157, 0xffff0000, v208
	v_lshlrev_b32_e32 v158, 16, v209
	v_and_b32_e32 v159, 0xffff0000, v209
	v_pk_fma_f32 v[2:3], v[32:33], v[136:137], v[44:45]
	v_pk_fma_f32 v[4:5], v[34:35], v[138:139], v[46:47]
	v_pk_fma_f32 v[6:7], v[48:49], v[140:141], v[60:61]
	v_pk_fma_f32 v[8:9], v[50:51], v[142:143], v[62:63]
	v_pk_fma_f32 v[2:3], v[36:37], v[144:145], v[2:3]
	v_pk_fma_f32 v[4:5], v[38:39], v[146:147], v[4:5]
	v_pk_fma_f32 v[6:7], v[52:53], v[148:149], v[6:7]
	v_pk_fma_f32 v[8:9], v[54:55], v[150:151], v[8:9]
	v_pk_fma_f32 v[2:3], v[40:41], v[152:153], v[2:3]
	v_pk_fma_f32 v[4:5], v[42:43], v[154:155], v[4:5]
	v_pk_fma_f32 v[6:7], v[56:57], v[156:157], v[6:7]
	v_pk_fma_f32 v[8:9], v[58:59], v[158:159], v[8:9]
	v_pk_mul_f32 v[10:11], v[2:3], v[160:161]
	v_pk_mul_f32 v[12:13], v[4:5], v[160:161]
	v_exp_f32_e32 v10, v10
	v_exp_f32_e32 v11, v11
	v_exp_f32_e32 v12, v12
	v_exp_f32_e32 v13, v13
	v_pk_add_f32 v[10:11], v[10:11], v[162:163]
	v_pk_add_f32 v[12:13], v[12:13], v[162:163]
	v_rcp_f32_e32 v10, v10
	v_rcp_f32_e32 v11, v11
	v_rcp_f32_e32 v12, v12
	v_rcp_f32_e32 v13, v13
	v_pk_mul_f32 v[10:11], v[2:3], v[10:11]
	v_pk_mul_f32 v[12:13], v[4:5], v[12:13]
	v_pk_mul_f32 v[10:11], v[6:7], v[10:11]
	v_pk_mul_f32 v[12:13], v[8:9], v[12:13]
	v_cvt_pk_bf16_f32 v14, v10, v11
	v_cvt_pk_bf16_f32 v15, v12, v13
	global_store_dwordx2 v28, v[14:15], s[10:11]
	s_add_u32 s10, s10, 0x1600
	s_addc_u32 s11, s11, 0
	global_store_dwordx4 v30, v[152:155], s[4:5]
	global_store_dwordx4 v31, v[156:159], s[4:5]
.Lffn_done:
.LBB0_118:
	s_or_b64 exec, exec, s[18:19]
	s_mov_b64 s[0:1], -1
	s_mov_b64 s[4:5], 0
